# a28: as a20 but GEMM priority lowered after the first 4 MFMAs of the next k-tile part
# baseline (speedup 1.0000x reference)
; #define GBAR() do { asm volatile("s_waitcnt vmcnt(0) lgkmcnt(0)" ::: "memory"); __builtin_amdgcn_s_barrier(); } while (0)
; template <int EPI, bool GUARD>
; DEVI void gemm_tile(const Params& p, const bf16_t* __restrict__ A, int lda, const bf16_t* __restrict__ Bt, int ldb, int K,
;                           int row_base, int row_lo, int row_hi, int tile_n, int layer, int which, char* lds) {
;     ...
;   const int swz = c16 >> 1;
;   int koff[2];
; #pragma unroll
;   for (int ks = 0; ks < 2; ++ks) koff[ks] = ((ks * 4 + q4) ^ swz) << 4;
;   const int arow = (wr * 64 + c16) * 128, brow = 16384 + (wc * 64 + c16) * 128;
;     ...
;   GISSUE(0, 0); GBAR();
;   for (int k0 = 0; k0 < K; k0 += 128) {
;     GISSUE(k0 + 64, 1);
;     KSTEPS(0);
;     GBAR();
;     if (k0 + 128 < K) GISSUE(k0 + 128, 0);
;     KSTEPS(1);
;     GBAR();
;   }
.LBB0_536:
	ds_read_b128 v[82:85], v64 offset:32768
	ds_read_b128 v[86:89], v105 offset:49152
	ds_read_b128 v[90:93], v64 offset:34816
	ds_read_b128 v[94:97], v105 offset:51200
	ds_read_b128 v[108:111], v105 offset:53248
	ds_read_b128 v[112:115], v105 offset:55296
	s_addk_i32 s61, 0x80
	s_waitcnt lgkmcnt(0)
	v_mfma_f32_16x16x32_bf16 v[0:3], v[82:85], v[86:89], v[0:3]
	s_add_u32 s16, s16, 0x100
	s_addc_u32 s17, s17, 0
	s_andn2_b64 vcc, exec, s[18:19]
	v_mfma_f32_16x16x32_bf16 v[4:7], v[82:85], v[94:97], v[4:7]
	v_mfma_f32_16x16x32_bf16 v[8:11], v[82:85], v[108:111], v[8:11]
	v_mfma_f32_16x16x32_bf16 v[12:15], v[82:85], v[112:115], v[12:15]
	s_setprio 0
	v_mfma_f32_16x16x32_bf16 v[16:19], v[90:93], v[86:89], v[16:19]
	v_mfma_f32_16x16x32_bf16 v[20:23], v[90:93], v[94:97], v[20:23]
	v_mfma_f32_16x16x32_bf16 v[24:27], v[90:93], v[108:111], v[24:27]
	v_mfma_f32_16x16x32_bf16 v[28:31], v[90:93], v[112:115], v[28:31]
	ds_read_b128 v[82:85], v64 offset:36864
	ds_read_b128 v[90:93], v64 offset:38912
	s_waitcnt lgkmcnt(0)
	v_mfma_f32_16x16x32_bf16 v[116:119], v[82:85], v[86:89], v[32:35]
	s_nop 2
	ds_read_b128 v[32:35], v106 offset:32768
	v_mfma_f32_16x16x32_bf16 v[120:123], v[82:85], v[94:97], v[36:39]
	v_mfma_f32_16x16x32_bf16 v[124:127], v[82:85], v[108:111], v[40:43]
	v_mfma_f32_16x16x32_bf16 v[82:85], v[82:85], v[112:115], v[44:47]
	v_mfma_f32_16x16x32_bf16 v[86:89], v[90:93], v[86:89], v[48:51]
	v_mfma_f32_16x16x32_bf16 v[94:97], v[90:93], v[94:97], v[52:55]
	v_mfma_f32_16x16x32_bf16 v[108:111], v[90:93], v[108:111], v[56:59]
	v_mfma_f32_16x16x32_bf16 v[90:93], v[90:93], v[112:115], v[60:63]
	ds_read_b128 v[112:115], v107 offset:49152
	ds_read_b128 v[36:39], v106 offset:34816
	ds_read_b128 v[128:131], v107 offset:51200
	ds_read_b128 v[132:135], v107 offset:53248
	ds_read_b128 v[136:139], v107 offset:55296
	s_waitcnt lgkmcnt(0)
	v_mfma_f32_16x16x32_bf16 v[56:59], v[32:35], v[112:115], v[0:3]
	v_mfma_f32_16x16x32_bf16 v[60:63], v[32:35], v[132:135], v[8:11]
	s_nop 1
	ds_read_b128 v[0:3], v106 offset:36864
	ds_read_b128 v[8:11], v106 offset:38912
	s_waitcnt vmcnt(0) lgkmcnt(0)
	s_barrier
	s_cbranch_vccz .Lge0_exit1
	s_setprio 1
	v_mfma_f32_16x16x32_bf16 v[48:51], v[32:35], v[128:131], v[4:7]
	s_add_i32 m0, s45, 0x8000
	v_lshl_add_u64 v[246:247], s[16:17], 0, v[66:67]
	v_lshl_add_u64 v[246:247], v[246:247], 0, s[4:5]
	global_load_lds_dwordx4 v[246:247], off
	v_mfma_f32_16x16x32_bf16 v[52:55], v[32:35], v[136:139], v[12:15]
	s_add_i32 m0, s45, 0xc000
	v_lshl_add_u64 v[246:247], s[16:17], 0, v[74:75]
	v_lshl_add_u64 v[246:247], v[246:247], 0, s[6:7]
	global_load_lds_dwordx4 v[246:247], off
	v_mfma_f32_16x16x32_bf16 v[40:43], v[36:39], v[112:115], v[16:19]
	s_add_i32 m0, s45, 0x8400
	v_lshl_add_u64 v[246:247], s[16:17], 0, v[68:69]
	v_lshl_add_u64 v[246:247], v[246:247], 0, s[4:5]
	global_load_lds_dwordx4 v[246:247], off
	v_mfma_f32_16x16x32_bf16 v[32:35], v[36:39], v[128:131], v[20:23]
	s_add_i32 m0, s45, 0xc400
	v_lshl_add_u64 v[246:247], s[16:17], 0, v[76:77]
	v_lshl_add_u64 v[246:247], v[246:247], 0, s[6:7]
	global_load_lds_dwordx4 v[246:247], off
	v_mfma_f32_16x16x32_bf16 v[44:47], v[36:39], v[132:135], v[24:27]
	s_add_i32 m0, s45, 0x8800
	v_lshl_add_u64 v[246:247], s[16:17], 0, v[70:71]
	v_lshl_add_u64 v[246:247], v[246:247], 0, s[4:5]
	global_load_lds_dwordx4 v[246:247], off
	v_mfma_f32_16x16x32_bf16 v[36:39], v[36:39], v[136:139], v[28:31]
	s_add_i32 m0, s45, 0xc800
	v_lshl_add_u64 v[246:247], s[16:17], 0, v[78:79]
	v_lshl_add_u64 v[246:247], v[246:247], 0, s[6:7]
	global_load_lds_dwordx4 v[246:247], off
	s_waitcnt lgkmcnt(0)
	v_mfma_f32_16x16x32_bf16 v[24:27], v[0:3], v[112:115], v[116:119]
	s_add_i32 m0, s45, 0x8c00
	v_lshl_add_u64 v[246:247], s[16:17], 0, v[72:73]
	v_lshl_add_u64 v[246:247], v[246:247], 0, s[4:5]
	global_load_lds_dwordx4 v[246:247], off
	v_mfma_f32_16x16x32_bf16 v[16:19], v[0:3], v[128:131], v[120:123]
	s_add_i32 m0, s45, 0xcc00
	v_lshl_add_u64 v[246:247], s[16:17], 0, v[80:81]
	v_lshl_add_u64 v[246:247], v[246:247], 0, s[6:7]
	global_load_lds_dwordx4 v[246:247], off
	v_mfma_f32_16x16x32_bf16 v[28:31], v[0:3], v[132:135], v[124:127]
	v_mfma_f32_16x16x32_bf16 v[20:23], v[0:3], v[136:139], v[82:85]
	v_mfma_f32_16x16x32_bf16 v[4:7], v[8:11], v[112:115], v[86:89]
	v_mfma_f32_16x16x32_bf16 v[0:3], v[8:11], v[128:131], v[94:97]
	v_mfma_f32_16x16x32_bf16 v[12:15], v[8:11], v[132:135], v[108:111]
	v_mfma_f32_16x16x32_bf16 v[8:11], v[8:11], v[136:139], v[90:93]
	s_cmpk_gt_u32 s61, 0x37f
	s_branch .Lge0_k0

; #define GBAR() do { asm volatile("s_waitcnt vmcnt(0) lgkmcnt(0)" ::: "memory"); __builtin_amdgcn_s_barrier(); } while (0)
; template <int EPI, bool GUARD>
; DEVI void gemm_tile(const Params& p, const bf16_t* __restrict__ A, int lda, const bf16_t* __restrict__ Bt, int ldb, int K,
;                           int row_base, int row_lo, int row_hi, int tile_n, int layer, int which, char* lds) {
;     ...
;   const int swz = c16 >> 1;
;   int koff[2];
; #pragma unroll
;   for (int ks = 0; ks < 2; ++ks) koff[ks] = ((ks * 4 + q4) ^ swz) << 4;
;   const int arow = (wr * 64 + c16) * 128, brow = 16384 + (wc * 64 + c16) * 128;
;     ...
;   GISSUE(0, 0); GBAR();
;   for (int k0 = 0; k0 < K; k0 += 128) {
;     GISSUE(k0 + 64, 1);
;     KSTEPS(0);
;     GBAR();
;     if (k0 + 128 < K) GISSUE(k0 + 128, 0);
;     KSTEPS(1);
;     GBAR();
;   }
.Lge0_k0:
	ds_read_b128 v[108:111], v64
	ds_read_b128 v[112:115], v105 offset:16384
	ds_read_b128 v[116:119], v64 offset:2048
	ds_read_b128 v[120:123], v105 offset:18432
	ds_read_b128 v[124:127], v105 offset:20480
	ds_read_b128 v[128:131], v105 offset:22528
	s_waitcnt lgkmcnt(0)
	v_mfma_f32_16x16x32_bf16 v[56:59], v[108:111], v[112:115], v[56:59]
	s_cselect_b64 s[18:19], -1, 0
	s_and_b64 vcc, exec, s[18:19]
	v_mfma_f32_16x16x32_bf16 v[48:51], v[108:111], v[120:123], v[48:51]
	v_mfma_f32_16x16x32_bf16 v[60:63], v[108:111], v[124:127], v[60:63]
	v_mfma_f32_16x16x32_bf16 v[52:55], v[108:111], v[128:131], v[52:55]
	s_setprio 0
	v_mfma_f32_16x16x32_bf16 v[40:43], v[116:119], v[112:115], v[40:43]
	v_mfma_f32_16x16x32_bf16 v[32:35], v[116:119], v[120:123], v[32:35]
	v_mfma_f32_16x16x32_bf16 v[44:47], v[116:119], v[124:127], v[44:47]
	v_mfma_f32_16x16x32_bf16 v[36:39], v[116:119], v[128:131], v[36:39]
	ds_read_b128 v[108:111], v64 offset:4096
	ds_read_b128 v[116:119], v64 offset:6144
	s_waitcnt lgkmcnt(0)
	v_mfma_f32_16x16x32_bf16 v[140:143], v[108:111], v[124:127], v[28:31]
	v_mfma_f32_16x16x32_bf16 v[124:127], v[116:119], v[124:127], v[12:15]
	s_nop 2
	ds_read_b128 v[12:15], v106
	v_mfma_f32_16x16x32_bf16 v[132:135], v[108:111], v[112:115], v[24:27]
	v_mfma_f32_16x16x32_bf16 v[136:139], v[108:111], v[120:123], v[16:19]
	v_mfma_f32_16x16x32_bf16 v[108:111], v[108:111], v[128:131], v[20:23]
	v_mfma_f32_16x16x32_bf16 v[112:115], v[116:119], v[112:115], v[4:7]
	v_mfma_f32_16x16x32_bf16 v[120:123], v[116:119], v[120:123], v[0:3]
	v_mfma_f32_16x16x32_bf16 v[116:119], v[116:119], v[128:131], v[8:11]
	ds_read_b128 v[128:131], v107 offset:16384
	ds_read_b128 v[28:31], v106 offset:2048
	ds_read_b128 v[144:147], v107 offset:18432
	s_waitcnt lgkmcnt(0)
	v_mfma_f32_16x16x32_bf16 v[0:3], v[12:15], v[128:131], v[56:59]
	s_nop 2
	ds_read_b128 v[56:59], v107 offset:20480
	ds_read_b128 v[148:151], v107 offset:22528
	s_waitcnt lgkmcnt(0)
	v_mfma_f32_16x16x32_bf16 v[8:11], v[12:15], v[56:59], v[60:63]
	v_mfma_f32_16x16x32_bf16 v[24:27], v[28:31], v[56:59], v[44:47]
	s_nop 2
	ds_read_b128 v[44:47], v106 offset:4096
	ds_read_b128 v[60:63], v106 offset:6144
	s_waitcnt vmcnt(0) lgkmcnt(0)
	s_barrier
	s_cbranch_vccnz .Lge0_last0
	s_setprio 1
	v_mfma_f32_16x16x32_bf16 v[4:7], v[12:15], v[144:147], v[48:51]
	s_mov_b32 m0, s45
	v_lshl_add_u64 v[246:247], s[16:17], 0, v[66:67]
	v_lshl_add_u64 v[246:247], v[246:247], 0, s[8:9]
	global_load_lds_dwordx4 v[246:247], off
	v_mfma_f32_16x16x32_bf16 v[12:15], v[12:15], v[148:151], v[52:55]
	s_mov_b32 m0, s46
	v_lshl_add_u64 v[246:247], s[16:17], 0, v[74:75]
	v_lshl_add_u64 v[246:247], v[246:247], 0, s[12:13]
	global_load_lds_dwordx4 v[246:247], off
	v_mfma_f32_16x16x32_bf16 v[16:19], v[28:31], v[128:131], v[40:43]
	s_mov_b32 m0, s47
	v_lshl_add_u64 v[246:247], s[16:17], 0, v[68:69]
	v_lshl_add_u64 v[246:247], v[246:247], 0, s[8:9]
	global_load_lds_dwordx4 v[246:247], off
	v_mfma_f32_16x16x32_bf16 v[20:23], v[28:31], v[144:147], v[32:35]
	s_mov_b32 m0, s54
	v_lshl_add_u64 v[246:247], s[16:17], 0, v[76:77]
	v_lshl_add_u64 v[246:247], v[246:247], 0, s[12:13]
	global_load_lds_dwordx4 v[246:247], off
	v_mfma_f32_16x16x32_bf16 v[28:31], v[28:31], v[148:151], v[36:39]
	s_mov_b32 m0, s55
	v_lshl_add_u64 v[246:247], s[16:17], 0, v[70:71]
	v_lshl_add_u64 v[246:247], v[246:247], 0, s[8:9]
	global_load_lds_dwordx4 v[246:247], off
	s_waitcnt lgkmcnt(0)
	v_mfma_f32_16x16x32_bf16 v[32:35], v[44:47], v[128:131], v[132:135]
	s_mov_b32 m0, s58
	v_lshl_add_u64 v[246:247], s[16:17], 0, v[78:79]
	v_lshl_add_u64 v[246:247], v[246:247], 0, s[12:13]
	global_load_lds_dwordx4 v[246:247], off
	v_mfma_f32_16x16x32_bf16 v[36:39], v[44:47], v[144:147], v[136:139]
	s_mov_b32 m0, s59
	v_lshl_add_u64 v[246:247], s[16:17], 0, v[72:73]
	v_lshl_add_u64 v[246:247], v[246:247], 0, s[8:9]
	global_load_lds_dwordx4 v[246:247], off
	v_mfma_f32_16x16x32_bf16 v[40:43], v[44:47], v[56:59], v[140:143]
	s_mov_b32 m0, s60
	v_lshl_add_u64 v[246:247], s[16:17], 0, v[80:81]
	v_lshl_add_u64 v[246:247], v[246:247], 0, s[12:13]
	global_load_lds_dwordx4 v[246:247], off
	v_mfma_f32_16x16x32_bf16 v[44:47], v[44:47], v[148:151], v[108:111]
	v_mfma_f32_16x16x32_bf16 v[48:51], v[60:63], v[128:131], v[112:115]
	v_mfma_f32_16x16x32_bf16 v[52:55], v[60:63], v[144:147], v[120:123]
	v_mfma_f32_16x16x32_bf16 v[56:59], v[60:63], v[56:59], v[124:127]
	v_mfma_f32_16x16x32_bf16 v[60:63], v[60:63], v[148:151], v[116:119]
	s_branch .LBB0_536

; #define GBAR() do { asm volatile("s_waitcnt vmcnt(0) lgkmcnt(0)" ::: "memory"); __builtin_amdgcn_s_barrier(); } while (0)
; template <int EPI, bool GUARD>
; DEVI void gemm_tile(const Params& p, const bf16_t* __restrict__ A, int lda, const bf16_t* __restrict__ Bt, int ldb, int K,
;                           int row_base, int row_lo, int row_hi, int tile_n, int layer, int which, char* lds) {
;     ...
;   const int swz = c16 >> 1;
;   int koff[2];
; #pragma unroll
;   for (int ks = 0; ks < 2; ++ks) koff[ks] = ((ks * 4 + q4) ^ swz) << 4;
;   const int arow = (wr * 64 + c16) * 128, brow = 16384 + (wc * 64 + c16) * 128;
;     ...
;   GISSUE(0, 0); GBAR();
;   for (int k0 = 0; k0 < K; k0 += 128) {
;     GISSUE(k0 + 64, 1);
;     KSTEPS(0);
;     GBAR();
;     if (k0 + 128 < K) GISSUE(k0 + 128, 0);
;     KSTEPS(1);
;     GBAR();
;   }
.LBB0_667:
	ds_read_b128 v[82:85], v64 offset:32768
	ds_read_b128 v[86:89], v111 offset:49152
	ds_read_b128 v[90:93], v64 offset:34816
	ds_read_b128 v[94:97], v111 offset:51200
	ds_read_b128 v[114:117], v111 offset:53248
	ds_read_b128 v[118:121], v111 offset:55296
	s_addk_i32 s9, 0x80
	s_waitcnt lgkmcnt(0)
	v_mfma_f32_16x16x32_bf16 v[0:3], v[82:85], v[86:89], v[0:3]
	s_add_u32 s4, s4, 0x100
	s_addc_u32 s5, s5, 0
	s_and_b64 vcc, exec, s[6:7]
	v_mfma_f32_16x16x32_bf16 v[4:7], v[82:85], v[94:97], v[4:7]
	v_mfma_f32_16x16x32_bf16 v[8:11], v[82:85], v[114:117], v[8:11]
	v_mfma_f32_16x16x32_bf16 v[12:15], v[82:85], v[118:121], v[12:15]
	s_setprio 0
	v_mfma_f32_16x16x32_bf16 v[82:85], v[90:93], v[86:89], v[16:19]
	v_mfma_f32_16x16x32_bf16 v[20:23], v[90:93], v[94:97], v[20:23]
	v_mfma_f32_16x16x32_bf16 v[24:27], v[90:93], v[114:117], v[24:27]
	v_mfma_f32_16x16x32_bf16 v[28:31], v[90:93], v[118:121], v[28:31]
	ds_read_b128 v[16:19], v64 offset:36864
	ds_read_b128 v[90:93], v64 offset:38912
	s_waitcnt lgkmcnt(0)
	v_mfma_f32_16x16x32_bf16 v[122:125], v[16:19], v[86:89], v[32:35]
	v_mfma_f32_16x16x32_bf16 v[36:39], v[16:19], v[94:97], v[36:39]
	v_mfma_f32_16x16x32_bf16 v[40:43], v[16:19], v[114:117], v[40:43]
	v_mfma_f32_16x16x32_bf16 v[44:47], v[16:19], v[118:121], v[44:47]
	ds_read_b128 v[16:19], v112 offset:32768
	v_mfma_f32_16x16x32_bf16 v[86:89], v[90:93], v[86:89], v[48:51]
	v_mfma_f32_16x16x32_bf16 v[52:55], v[90:93], v[94:97], v[52:55]
	v_mfma_f32_16x16x32_bf16 v[56:59], v[90:93], v[114:117], v[56:59]
	v_mfma_f32_16x16x32_bf16 v[60:63], v[90:93], v[118:121], v[60:63]
	ds_read_b128 v[90:93], v113 offset:49152
	ds_read_b128 v[32:35], v112 offset:34816
	ds_read_b128 v[94:97], v113 offset:51200
	ds_read_b128 v[114:117], v113 offset:53248
	ds_read_b128 v[118:121], v113 offset:55296
	s_waitcnt lgkmcnt(0)
	v_mfma_f32_16x16x32_bf16 v[0:3], v[16:19], v[90:93], v[0:3]
	v_mfma_f32_16x16x32_bf16 v[4:7], v[16:19], v[94:97], v[4:7]
	v_mfma_f32_16x16x32_bf16 v[8:11], v[16:19], v[114:117], v[8:11]
	v_mfma_f32_16x16x32_bf16 v[16:19], v[16:19], v[118:121], v[12:15]
	v_mfma_f32_16x16x32_bf16 v[12:15], v[32:35], v[90:93], v[82:85]
	ds_read_b128 v[48:51], v112 offset:36864
	s_nop 1
	ds_read_b128 v[82:85], v112 offset:38912
	s_waitcnt vmcnt(0) lgkmcnt(0)
	s_barrier
	s_cbranch_vccnz .Lge1_exit1
	s_setprio 1
	v_mfma_f32_16x16x32_bf16 v[20:23], v[32:35], v[94:97], v[20:23]
	s_add_i32 m0, s69, 0x8000
	v_lshl_add_u64 v[246:247], s[4:5], 0, v[66:67]
	v_lshl_add_u64 v[246:247], v[246:247], 0, s[16:17]
	global_load_lds_dwordx4 v[246:247], off
	v_mfma_f32_16x16x32_bf16 v[24:27], v[32:35], v[114:117], v[24:27]
	s_add_i32 m0, s69, 0xc000
	v_lshl_add_u64 v[246:247], s[4:5], 0, v[74:75]
	v_lshl_add_u64 v[246:247], v[246:247], 0, s[18:19]
	global_load_lds_dwordx4 v[246:247], off
	v_mfma_f32_16x16x32_bf16 v[32:35], v[32:35], v[118:121], v[28:31]
	s_add_i32 m0, s69, 0x8400
	v_lshl_add_u64 v[246:247], s[4:5], 0, v[68:69]
	v_lshl_add_u64 v[246:247], v[246:247], 0, s[16:17]
	global_load_lds_dwordx4 v[246:247], off
	s_waitcnt lgkmcnt(0)
	v_mfma_f32_16x16x32_bf16 v[28:31], v[48:51], v[90:93], v[122:125]
	s_add_i32 m0, s69, 0xc400
	v_lshl_add_u64 v[246:247], s[4:5], 0, v[76:77]
	v_lshl_add_u64 v[246:247], v[246:247], 0, s[18:19]
	global_load_lds_dwordx4 v[246:247], off
	v_mfma_f32_16x16x32_bf16 v[36:39], v[48:51], v[94:97], v[36:39]
	s_add_i32 m0, s69, 0x8800
	v_lshl_add_u64 v[246:247], s[4:5], 0, v[70:71]
	v_lshl_add_u64 v[246:247], v[246:247], 0, s[16:17]
	global_load_lds_dwordx4 v[246:247], off
	v_mfma_f32_16x16x32_bf16 v[40:43], v[48:51], v[114:117], v[40:43]
	s_add_i32 m0, s69, 0xc800
	v_lshl_add_u64 v[246:247], s[4:5], 0, v[78:79]
	v_lshl_add_u64 v[246:247], v[246:247], 0, s[18:19]
	global_load_lds_dwordx4 v[246:247], off
	v_mfma_f32_16x16x32_bf16 v[48:51], v[48:51], v[118:121], v[44:47]
	s_add_i32 m0, s75, 0x8000
	v_lshl_add_u64 v[246:247], s[4:5], 0, v[72:73]
	v_lshl_add_u64 v[246:247], v[246:247], 0, s[16:17]
	global_load_lds_dwordx4 v[246:247], off
	v_mfma_f32_16x16x32_bf16 v[44:47], v[82:85], v[90:93], v[86:89]
	s_add_i32 m0, s75, 0xc000
	v_lshl_add_u64 v[246:247], s[4:5], 0, v[80:81]
	v_lshl_add_u64 v[246:247], v[246:247], 0, s[18:19]
	global_load_lds_dwordx4 v[246:247], off
	v_mfma_f32_16x16x32_bf16 v[52:55], v[82:85], v[94:97], v[52:55]
	v_mfma_f32_16x16x32_bf16 v[56:59], v[82:85], v[114:117], v[56:59]
	v_mfma_f32_16x16x32_bf16 v[60:63], v[82:85], v[118:121], v[60:63]
	s_cmpk_gt_u32 s9, 0x37f
	s_branch .Lge1_k0

; #define GBAR() do { asm volatile("s_waitcnt vmcnt(0) lgkmcnt(0)" ::: "memory"); __builtin_amdgcn_s_barrier(); } while (0)
; template <int EPI, bool GUARD>
; DEVI void gemm_tile(const Params& p, const bf16_t* __restrict__ A, int lda, const bf16_t* __restrict__ Bt, int ldb, int K,
;                           int row_base, int row_lo, int row_hi, int tile_n, int layer, int which, char* lds) {
;     ...
;   const int swz = c16 >> 1;
;   int koff[2];
; #pragma unroll
;   for (int ks = 0; ks < 2; ++ks) koff[ks] = ((ks * 4 + q4) ^ swz) << 4;
;   const int arow = (wr * 64 + c16) * 128, brow = 16384 + (wc * 64 + c16) * 128;
;     ...
;   GISSUE(0, 0); GBAR();
;   for (int k0 = 0; k0 < K; k0 += 128) {
;     GISSUE(k0 + 64, 1);
;     KSTEPS(0);
;     GBAR();
;     if (k0 + 128 < K) GISSUE(k0 + 128, 0);
;     KSTEPS(1);
;     GBAR();
;   }
.Lge1_k0:
	ds_read_b128 v[114:117], v64
	ds_read_b128 v[118:121], v111 offset:16384
	ds_read_b128 v[122:125], v64 offset:2048
	ds_read_b128 v[126:129], v111 offset:18432
	ds_read_b128 v[130:133], v111 offset:20480
	ds_read_b128 v[134:137], v111 offset:22528
	s_waitcnt lgkmcnt(0)
	v_mfma_f32_16x16x32_bf16 v[0:3], v[114:117], v[118:121], v[0:3]
	s_cselect_b64 s[6:7], -1, 0
	s_and_b64 vcc, exec, s[6:7]
	v_mfma_f32_16x16x32_bf16 v[4:7], v[114:117], v[126:129], v[4:7]
	v_mfma_f32_16x16x32_bf16 v[8:11], v[114:117], v[130:133], v[8:11]
	v_mfma_f32_16x16x32_bf16 v[16:19], v[114:117], v[134:137], v[16:19]
	s_setprio 0
	v_mfma_f32_16x16x32_bf16 v[114:117], v[122:125], v[118:121], v[12:15]
	v_mfma_f32_16x16x32_bf16 v[20:23], v[122:125], v[126:129], v[20:23]
	v_mfma_f32_16x16x32_bf16 v[24:27], v[122:125], v[130:133], v[24:27]
	v_mfma_f32_16x16x32_bf16 v[32:35], v[122:125], v[134:137], v[32:35]
	ds_read_b128 v[12:15], v64 offset:4096
	ds_read_b128 v[122:125], v64 offset:6144
	s_waitcnt lgkmcnt(0)
	v_mfma_f32_16x16x32_bf16 v[138:141], v[12:15], v[118:121], v[28:31]
	v_mfma_f32_16x16x32_bf16 v[36:39], v[12:15], v[126:129], v[36:39]
	v_mfma_f32_16x16x32_bf16 v[40:43], v[12:15], v[130:133], v[40:43]
	v_mfma_f32_16x16x32_bf16 v[48:51], v[12:15], v[134:137], v[48:51]
	ds_read_b128 v[12:15], v112
	v_mfma_f32_16x16x32_bf16 v[118:121], v[122:125], v[118:121], v[44:47]
	v_mfma_f32_16x16x32_bf16 v[52:55], v[122:125], v[126:129], v[52:55]
	v_mfma_f32_16x16x32_bf16 v[56:59], v[122:125], v[130:133], v[56:59]
	v_mfma_f32_16x16x32_bf16 v[60:63], v[122:125], v[134:137], v[60:63]
	ds_read_b128 v[122:125], v113 offset:16384
	ds_read_b128 v[28:31], v112 offset:2048
	ds_read_b128 v[126:129], v113 offset:18432
	ds_read_b128 v[130:133], v113 offset:20480
	ds_read_b128 v[134:137], v113 offset:22528
	s_waitcnt lgkmcnt(0)
	v_mfma_f32_16x16x32_bf16 v[0:3], v[12:15], v[122:125], v[0:3]
	v_mfma_f32_16x16x32_bf16 v[4:7], v[12:15], v[126:129], v[4:7]
	v_mfma_f32_16x16x32_bf16 v[8:11], v[12:15], v[130:133], v[8:11]
	v_mfma_f32_16x16x32_bf16 v[12:15], v[12:15], v[134:137], v[16:19]
	v_mfma_f32_16x16x32_bf16 v[16:19], v[28:31], v[122:125], v[114:117]
	ds_read_b128 v[44:47], v112 offset:4096
	s_nop 1
	ds_read_b128 v[114:117], v112 offset:6144
	s_waitcnt vmcnt(0) lgkmcnt(0)
	s_barrier
	s_cbranch_vccnz .Lge1_last0
	s_setprio 1
	v_mfma_f32_16x16x32_bf16 v[20:23], v[28:31], v[126:129], v[20:23]
	s_mov_b32 m0, s69
	v_lshl_add_u64 v[246:247], s[4:5], 0, v[66:67]
	v_lshl_add_u64 v[246:247], v[246:247], 0, s[26:27]
	global_load_lds_dwordx4 v[246:247], off
	v_mfma_f32_16x16x32_bf16 v[24:27], v[28:31], v[130:133], v[24:27]
	s_mov_b32 m0, s70
	v_lshl_add_u64 v[246:247], s[4:5], 0, v[74:75]
	v_lshl_add_u64 v[246:247], v[246:247], 0, s[34:35]
	global_load_lds_dwordx4 v[246:247], off
	v_mfma_f32_16x16x32_bf16 v[28:31], v[28:31], v[134:137], v[32:35]
	s_mov_b32 m0, s71
	v_lshl_add_u64 v[246:247], s[4:5], 0, v[68:69]
	v_lshl_add_u64 v[246:247], v[246:247], 0, s[26:27]
	global_load_lds_dwordx4 v[246:247], off
	s_waitcnt lgkmcnt(0)
	v_mfma_f32_16x16x32_bf16 v[32:35], v[44:47], v[122:125], v[138:141]
	s_mov_b32 m0, s72
	v_lshl_add_u64 v[246:247], s[4:5], 0, v[76:77]
	v_lshl_add_u64 v[246:247], v[246:247], 0, s[34:35]
	global_load_lds_dwordx4 v[246:247], off
	v_mfma_f32_16x16x32_bf16 v[36:39], v[44:47], v[126:129], v[36:39]
	s_mov_b32 m0, s73
	v_lshl_add_u64 v[246:247], s[4:5], 0, v[70:71]
	v_lshl_add_u64 v[246:247], v[246:247], 0, s[26:27]
	global_load_lds_dwordx4 v[246:247], off
	v_mfma_f32_16x16x32_bf16 v[40:43], v[44:47], v[130:133], v[40:43]
	s_mov_b32 m0, s74
	v_lshl_add_u64 v[246:247], s[4:5], 0, v[78:79]
	v_lshl_add_u64 v[246:247], v[246:247], 0, s[34:35]
	global_load_lds_dwordx4 v[246:247], off
	v_mfma_f32_16x16x32_bf16 v[44:47], v[44:47], v[134:137], v[48:51]
	s_mov_b32 m0, s75
	v_lshl_add_u64 v[246:247], s[4:5], 0, v[72:73]
	v_lshl_add_u64 v[246:247], v[246:247], 0, s[26:27]
	global_load_lds_dwordx4 v[246:247], off
	v_mfma_f32_16x16x32_bf16 v[48:51], v[114:117], v[122:125], v[118:121]
	s_mov_b32 m0, s76
	v_lshl_add_u64 v[246:247], s[4:5], 0, v[80:81]
	v_lshl_add_u64 v[246:247], v[246:247], 0, s[34:35]
	global_load_lds_dwordx4 v[246:247], off
	v_mfma_f32_16x16x32_bf16 v[52:55], v[114:117], v[126:129], v[52:55]
	v_mfma_f32_16x16x32_bf16 v[56:59], v[114:117], v[130:133], v[56:59]
	v_mfma_f32_16x16x32_bf16 v[60:63], v[114:117], v[134:137], v[60:63]
	s_branch .LBB0_667

; #define GBAR() do { asm volatile("s_waitcnt vmcnt(0) lgkmcnt(0)" ::: "memory"); __builtin_amdgcn_s_barrier(); } while (0)
; template <int EPI, bool GUARD>
; DEVI void gemm_tile(const Params& p, const bf16_t* __restrict__ A, int lda, const bf16_t* __restrict__ Bt, int ldb, int K,
;                           int row_base, int row_lo, int row_hi, int tile_n, int layer, int which, char* lds) {
;     ...
;   const int swz = c16 >> 1;
;   int koff[2];
; #pragma unroll
;   for (int ks = 0; ks < 2; ++ks) koff[ks] = ((ks * 4 + q4) ^ swz) << 4;
;   const int arow = (wr * 64 + c16) * 128, brow = 16384 + (wc * 64 + c16) * 128;
;     ...
;   GISSUE(0, 0); GBAR();
;   for (int k0 = 0; k0 < K; k0 += 128) {
;     GISSUE(k0 + 64, 1);
;     KSTEPS(0);
;     GBAR();
;     if (k0 + 128 < K) GISSUE(k0 + 128, 0);
;     KSTEPS(1);
;     GBAR();
;   }
.LBB0_745:
	ds_read_b128 v[82:85], v64 offset:32768
	ds_read_b128 v[86:89], v107 offset:49152
	ds_read_b128 v[90:93], v64 offset:34816
	ds_read_b128 v[94:97], v107 offset:51200
	ds_read_b128 v[110:113], v107 offset:53248
	ds_read_b128 v[114:117], v107 offset:55296
	s_addk_i32 s62, 0x80
	s_waitcnt lgkmcnt(0)
	v_mfma_f32_16x16x32_bf16 v[0:3], v[82:85], v[86:89], v[0:3]
	s_add_u32 s26, s26, 0x100
	s_addc_u32 s27, s27, 0
	s_andn2_b64 vcc, exec, s[34:35]
	v_mfma_f32_16x16x32_bf16 v[4:7], v[82:85], v[94:97], v[4:7]
	v_mfma_f32_16x16x32_bf16 v[8:11], v[82:85], v[110:113], v[8:11]
	v_mfma_f32_16x16x32_bf16 v[12:15], v[82:85], v[114:117], v[12:15]
	s_setprio 0
	v_mfma_f32_16x16x32_bf16 v[16:19], v[90:93], v[86:89], v[16:19]
	v_mfma_f32_16x16x32_bf16 v[20:23], v[90:93], v[94:97], v[20:23]
	v_mfma_f32_16x16x32_bf16 v[24:27], v[90:93], v[110:113], v[24:27]
	v_mfma_f32_16x16x32_bf16 v[28:31], v[90:93], v[114:117], v[28:31]
	ds_read_b128 v[82:85], v64 offset:36864
	ds_read_b128 v[90:93], v64 offset:38912
	s_waitcnt lgkmcnt(0)
	v_mfma_f32_16x16x32_bf16 v[118:121], v[82:85], v[86:89], v[32:35]
	s_nop 2
	ds_read_b128 v[32:35], v108 offset:32768
	v_mfma_f32_16x16x32_bf16 v[122:125], v[82:85], v[94:97], v[36:39]
	v_mfma_f32_16x16x32_bf16 v[126:129], v[82:85], v[110:113], v[40:43]
	v_mfma_f32_16x16x32_bf16 v[82:85], v[82:85], v[114:117], v[44:47]
	v_mfma_f32_16x16x32_bf16 v[86:89], v[90:93], v[86:89], v[48:51]
	v_mfma_f32_16x16x32_bf16 v[94:97], v[90:93], v[94:97], v[52:55]
	v_mfma_f32_16x16x32_bf16 v[110:113], v[90:93], v[110:113], v[56:59]
	v_mfma_f32_16x16x32_bf16 v[90:93], v[90:93], v[114:117], v[60:63]
	ds_read_b128 v[114:117], v109 offset:49152
	ds_read_b128 v[130:133], v108 offset:34816
	ds_read_b128 v[134:137], v109 offset:51200
	ds_read_b128 v[138:141], v109 offset:53248
	ds_read_b128 v[142:145], v109 offset:55296
	s_waitcnt lgkmcnt(0)
	v_mfma_f32_16x16x32_bf16 v[60:63], v[32:35], v[114:117], v[0:3]
	v_mfma_f32_16x16x32_bf16 v[52:55], v[32:35], v[138:141], v[8:11]
	s_nop 1
	ds_read_b128 v[0:3], v108 offset:36864
	ds_read_b128 v[8:11], v108 offset:38912
	s_waitcnt vmcnt(0) lgkmcnt(0)
	s_barrier
	s_cbranch_vccz .Lge2_exit1
	s_setprio 1
	v_mfma_f32_16x16x32_bf16 v[56:59], v[32:35], v[134:137], v[4:7]
	s_mov_b32 m0, s63
	v_lshl_add_u64 v[246:247], s[26:27], 0, v[66:67]
	v_lshl_add_u64 v[246:247], v[246:247], 0, s[4:5]
	global_load_lds_dwordx4 v[246:247], off
	v_mfma_f32_16x16x32_bf16 v[48:51], v[32:35], v[142:145], v[12:15]
	s_mov_b32 m0, s72
	v_lshl_add_u64 v[246:247], s[26:27], 0, v[74:75]
	v_lshl_add_u64 v[246:247], v[246:247], 0, s[6:7]
	global_load_lds_dwordx4 v[246:247], off
	v_mfma_f32_16x16x32_bf16 v[44:47], v[130:133], v[114:117], v[16:19]
	s_mov_b32 m0, s68
	v_lshl_add_u64 v[246:247], s[26:27], 0, v[68:69]
	v_lshl_add_u64 v[246:247], v[246:247], 0, s[4:5]
	global_load_lds_dwordx4 v[246:247], off
	v_mfma_f32_16x16x32_bf16 v[40:43], v[130:133], v[134:137], v[20:23]
	s_mov_b32 m0, s69
	v_lshl_add_u64 v[246:247], s[26:27], 0, v[76:77]
	v_lshl_add_u64 v[246:247], v[246:247], 0, s[6:7]
	global_load_lds_dwordx4 v[246:247], off
	v_mfma_f32_16x16x32_bf16 v[36:39], v[130:133], v[138:141], v[24:27]
	s_mov_b32 m0, s70
	v_lshl_add_u64 v[246:247], s[26:27], 0, v[70:71]
	v_lshl_add_u64 v[246:247], v[246:247], 0, s[4:5]
	global_load_lds_dwordx4 v[246:247], off
	v_mfma_f32_16x16x32_bf16 v[32:35], v[130:133], v[142:145], v[28:31]
	s_mov_b32 m0, s71
	v_lshl_add_u64 v[246:247], s[26:27], 0, v[78:79]
	v_lshl_add_u64 v[246:247], v[246:247], 0, s[6:7]
	global_load_lds_dwordx4 v[246:247], off
	s_waitcnt lgkmcnt(0)
	v_mfma_f32_16x16x32_bf16 v[28:31], v[0:3], v[114:117], v[118:121]
	s_mov_b32 m0, s73
	v_lshl_add_u64 v[246:247], s[26:27], 0, v[72:73]
	v_lshl_add_u64 v[246:247], v[246:247], 0, s[4:5]
	global_load_lds_dwordx4 v[246:247], off
	v_mfma_f32_16x16x32_bf16 v[24:27], v[0:3], v[134:137], v[122:125]
	s_mov_b32 m0, s74
	v_lshl_add_u64 v[246:247], s[26:27], 0, v[80:81]
	v_lshl_add_u64 v[246:247], v[246:247], 0, s[6:7]
	global_load_lds_dwordx4 v[246:247], off
	v_mfma_f32_16x16x32_bf16 v[16:19], v[0:3], v[138:141], v[126:129]
	v_mfma_f32_16x16x32_bf16 v[12:15], v[0:3], v[142:145], v[82:85]
	v_mfma_f32_16x16x32_bf16 v[4:7], v[8:11], v[114:117], v[86:89]
	v_mfma_f32_16x16x32_bf16 v[0:3], v[8:11], v[134:137], v[94:97]
	v_mfma_f32_16x16x32_bf16 v[20:23], v[8:11], v[138:141], v[110:113]
	v_mfma_f32_16x16x32_bf16 v[8:11], v[8:11], v[142:145], v[90:93]
	s_cmpk_gt_u32 s62, 0xa7f
	s_cselect_b64 s[34:35], -1, 0
	s_and_b64 vcc, exec, s[34:35]
	s_branch .Lge2_k0

; #define GBAR() do { asm volatile("s_waitcnt vmcnt(0) lgkmcnt(0)" ::: "memory"); __builtin_amdgcn_s_barrier(); } while (0)
; template <int EPI, bool GUARD>
; DEVI void gemm_tile(const Params& p, const bf16_t* __restrict__ A, int lda, const bf16_t* __restrict__ Bt, int ldb, int K,
;                           int row_base, int row_lo, int row_hi, int tile_n, int layer, int which, char* lds) {
;     ...
;   const int swz = c16 >> 1;
;   int koff[2];
; #pragma unroll
;   for (int ks = 0; ks < 2; ++ks) koff[ks] = ((ks * 4 + q4) ^ swz) << 4;
;   const int arow = (wr * 64 + c16) * 128, brow = 16384 + (wc * 64 + c16) * 128;
;     ...
;   GISSUE(0, 0); GBAR();
;   for (int k0 = 0; k0 < K; k0 += 128) {
;     GISSUE(k0 + 64, 1);
;     KSTEPS(0);
;     GBAR();
;     if (k0 + 128 < K) GISSUE(k0 + 128, 0);
;     KSTEPS(1);
;     GBAR();
;   }
.Lge2_k0:
	ds_read_b128 v[110:113], v64
	ds_read_b128 v[114:117], v107 offset:16384
	ds_read_b128 v[118:121], v64 offset:2048
	ds_read_b128 v[122:125], v107 offset:18432
	ds_read_b128 v[126:129], v107 offset:20480
	ds_read_b128 v[130:133], v107 offset:22528
	s_waitcnt lgkmcnt(0)
	v_mfma_f32_16x16x32_bf16 v[60:63], v[110:113], v[114:117], v[60:63]
	v_mfma_f32_16x16x32_bf16 v[56:59], v[110:113], v[122:125], v[56:59]
	v_mfma_f32_16x16x32_bf16 v[52:55], v[110:113], v[126:129], v[52:55]
	v_mfma_f32_16x16x32_bf16 v[48:51], v[110:113], v[130:133], v[48:51]
	s_setprio 0
	v_mfma_f32_16x16x32_bf16 v[44:47], v[118:121], v[114:117], v[44:47]
	v_mfma_f32_16x16x32_bf16 v[40:43], v[118:121], v[122:125], v[40:43]
	v_mfma_f32_16x16x32_bf16 v[36:39], v[118:121], v[126:129], v[36:39]
	v_mfma_f32_16x16x32_bf16 v[32:35], v[118:121], v[130:133], v[32:35]
	ds_read_b128 v[110:113], v64 offset:4096
	ds_read_b128 v[118:121], v64 offset:6144
	s_waitcnt lgkmcnt(0)
	v_mfma_f32_16x16x32_bf16 v[134:137], v[110:113], v[114:117], v[28:31]
	v_mfma_f32_16x16x32_bf16 v[138:141], v[110:113], v[122:125], v[24:27]
	v_mfma_f32_16x16x32_bf16 v[142:145], v[110:113], v[126:129], v[16:19]
	v_mfma_f32_16x16x32_bf16 v[110:113], v[110:113], v[130:133], v[12:15]
	s_nop 2
	ds_read_b128 v[12:15], v108
	v_mfma_f32_16x16x32_bf16 v[114:117], v[118:121], v[114:117], v[4:7]
	v_mfma_f32_16x16x32_bf16 v[122:125], v[118:121], v[122:125], v[0:3]
	v_mfma_f32_16x16x32_bf16 v[126:129], v[118:121], v[126:129], v[20:23]
	v_mfma_f32_16x16x32_bf16 v[118:121], v[118:121], v[130:133], v[8:11]
	ds_read_b128 v[130:133], v109 offset:16384
	ds_read_b128 v[28:31], v108 offset:2048
	ds_read_b128 v[146:149], v109 offset:18432
	s_waitcnt lgkmcnt(0)
	v_mfma_f32_16x16x32_bf16 v[0:3], v[12:15], v[130:133], v[60:63]
	v_mfma_f32_16x16x32_bf16 v[4:7], v[12:15], v[146:149], v[56:59]
	s_nop 2
	ds_read_b128 v[56:59], v109 offset:20480
	ds_read_b128 v[60:63], v109 offset:22528
	v_mfma_f32_16x16x32_bf16 v[16:19], v[28:31], v[130:133], v[44:47]
	s_nop 2
	ds_read_b128 v[44:47], v108 offset:4096
	ds_read_b128 v[150:153], v108 offset:6144
	s_waitcnt vmcnt(0) lgkmcnt(0)
	s_barrier
	s_cbranch_vccnz .Lge2_last0
	s_setprio 1
	s_waitcnt lgkmcnt(0)
	v_mfma_f32_16x16x32_bf16 v[8:11], v[12:15], v[56:59], v[52:55]
	s_mov_b32 m0, s54
	v_lshl_add_u64 v[246:247], s[26:27], 0, v[66:67]
	v_lshl_add_u64 v[246:247], v[246:247], 0, s[8:9]
	global_load_lds_dwordx4 v[246:247], off
	v_mfma_f32_16x16x32_bf16 v[12:15], v[12:15], v[60:63], v[48:51]
	s_mov_b32 m0, s55
	v_lshl_add_u64 v[246:247], s[26:27], 0, v[74:75]
	v_lshl_add_u64 v[246:247], v[246:247], 0, s[16:17]
	global_load_lds_dwordx4 v[246:247], off
	v_mfma_f32_16x16x32_bf16 v[20:23], v[28:31], v[146:149], v[40:43]
	s_mov_b32 m0, s56
	v_lshl_add_u64 v[246:247], s[26:27], 0, v[68:69]
	v_lshl_add_u64 v[246:247], v[246:247], 0, s[8:9]
	global_load_lds_dwordx4 v[246:247], off
	v_mfma_f32_16x16x32_bf16 v[24:27], v[28:31], v[56:59], v[36:39]
	s_mov_b32 m0, s57
	v_lshl_add_u64 v[246:247], s[26:27], 0, v[76:77]
	v_lshl_add_u64 v[246:247], v[246:247], 0, s[16:17]
	global_load_lds_dwordx4 v[246:247], off
	v_mfma_f32_16x16x32_bf16 v[28:31], v[28:31], v[60:63], v[32:35]
	s_mov_b32 m0, s58
	v_lshl_add_u64 v[246:247], s[26:27], 0, v[70:71]
	v_lshl_add_u64 v[246:247], v[246:247], 0, s[8:9]
	global_load_lds_dwordx4 v[246:247], off
	v_mfma_f32_16x16x32_bf16 v[32:35], v[44:47], v[130:133], v[134:137]
	s_mov_b32 m0, s59
	v_lshl_add_u64 v[246:247], s[26:27], 0, v[78:79]
	v_lshl_add_u64 v[246:247], v[246:247], 0, s[16:17]
	global_load_lds_dwordx4 v[246:247], off
	v_mfma_f32_16x16x32_bf16 v[36:39], v[44:47], v[146:149], v[138:141]
	s_mov_b32 m0, s60
	v_lshl_add_u64 v[246:247], s[26:27], 0, v[72:73]
	v_lshl_add_u64 v[246:247], v[246:247], 0, s[8:9]
	global_load_lds_dwordx4 v[246:247], off
	v_mfma_f32_16x16x32_bf16 v[40:43], v[44:47], v[56:59], v[142:145]
	s_mov_b32 m0, s61
	v_lshl_add_u64 v[246:247], s[26:27], 0, v[80:81]
	v_lshl_add_u64 v[246:247], v[246:247], 0, s[16:17]
	global_load_lds_dwordx4 v[246:247], off
	v_mfma_f32_16x16x32_bf16 v[44:47], v[44:47], v[60:63], v[110:113]
	v_mfma_f32_16x16x32_bf16 v[48:51], v[150:153], v[130:133], v[114:117]
	v_mfma_f32_16x16x32_bf16 v[52:55], v[150:153], v[146:149], v[122:125]
	v_mfma_f32_16x16x32_bf16 v[56:59], v[150:153], v[56:59], v[126:129]
	v_mfma_f32_16x16x32_bf16 v[60:63], v[150:153], v[60:63], v[118:121]
	s_branch .LBB0_745

; #define GBAR() do { asm volatile("s_waitcnt vmcnt(0) lgkmcnt(0)" ::: "memory"); __builtin_amdgcn_s_barrier(); } while (0)
; template <int EPI, bool GUARD>
; DEVI void gemm_tile(const Params& p, const bf16_t* __restrict__ A, int lda, const bf16_t* __restrict__ Bt, int ldb, int K,
;                           int row_base, int row_lo, int row_hi, int tile_n, int layer, int which, char* lds) {
;     ...
;   const int swz = c16 >> 1;
;   int koff[2];
; #pragma unroll
;   for (int ks = 0; ks < 2; ++ks) koff[ks] = ((ks * 4 + q4) ^ swz) << 4;
;   const int arow = (wr * 64 + c16) * 128, brow = 16384 + (wc * 64 + c16) * 128;
;     ...
;   GISSUE(0, 0); GBAR();
;   for (int k0 = 0; k0 < K; k0 += 128) {
;     GISSUE(k0 + 64, 1);
;     KSTEPS(0);
;     GBAR();
;     if (k0 + 128 < K) GISSUE(k0 + 128, 0);
;     KSTEPS(1);
;     GBAR();
;   }
.LBB0_878:
	ds_read_b128 v[80:83], v101 offset:32768
	ds_read_b128 v[84:87], v102 offset:49152
	ds_read_b128 v[88:91], v101 offset:34816
	ds_read_b128 v[92:95], v102 offset:51200
	ds_read_b128 v[106:109], v102 offset:53248
	ds_read_b128 v[110:113], v102 offset:55296
	s_addk_i32 s85, 0x80
	s_waitcnt lgkmcnt(0)
	v_mfma_f32_16x16x32_bf16 v[0:3], v[80:83], v[84:87], v[0:3]
	s_add_u32 s4, s4, 0x100
	s_addc_u32 s5, s5, 0
	s_and_b64 vcc, exec, s[52:53]
	v_mfma_f32_16x16x32_bf16 v[4:7], v[80:83], v[92:95], v[4:7]
	v_mfma_f32_16x16x32_bf16 v[8:11], v[80:83], v[106:109], v[8:11]
	v_mfma_f32_16x16x32_bf16 v[12:15], v[80:83], v[110:113], v[12:15]
	s_setprio 0
	v_mfma_f32_16x16x32_bf16 v[80:83], v[88:91], v[84:87], v[16:19]
	v_mfma_f32_16x16x32_bf16 v[20:23], v[88:91], v[92:95], v[20:23]
	v_mfma_f32_16x16x32_bf16 v[24:27], v[88:91], v[106:109], v[24:27]
	v_mfma_f32_16x16x32_bf16 v[28:31], v[88:91], v[110:113], v[28:31]
	ds_read_b128 v[16:19], v101 offset:36864
	ds_read_b128 v[88:91], v101 offset:38912
	s_waitcnt lgkmcnt(0)
	v_mfma_f32_16x16x32_bf16 v[114:117], v[16:19], v[84:87], v[32:35]
	v_mfma_f32_16x16x32_bf16 v[36:39], v[16:19], v[92:95], v[36:39]
	v_mfma_f32_16x16x32_bf16 v[40:43], v[16:19], v[106:109], v[40:43]
	v_mfma_f32_16x16x32_bf16 v[44:47], v[16:19], v[110:113], v[44:47]
	ds_read_b128 v[16:19], v103 offset:32768
	v_mfma_f32_16x16x32_bf16 v[84:87], v[88:91], v[84:87], v[48:51]
	v_mfma_f32_16x16x32_bf16 v[52:55], v[88:91], v[92:95], v[52:55]
	v_mfma_f32_16x16x32_bf16 v[56:59], v[88:91], v[106:109], v[56:59]
	v_mfma_f32_16x16x32_bf16 v[60:63], v[88:91], v[110:113], v[60:63]
	ds_read_b128 v[88:91], v104 offset:49152
	ds_read_b128 v[32:35], v103 offset:34816
	ds_read_b128 v[92:95], v104 offset:51200
	ds_read_b128 v[106:109], v104 offset:53248
	ds_read_b128 v[110:113], v104 offset:55296
	s_waitcnt lgkmcnt(0)
	v_mfma_f32_16x16x32_bf16 v[0:3], v[16:19], v[88:91], v[0:3]
	v_mfma_f32_16x16x32_bf16 v[4:7], v[16:19], v[92:95], v[4:7]
	v_mfma_f32_16x16x32_bf16 v[8:11], v[16:19], v[106:109], v[8:11]
	v_mfma_f32_16x16x32_bf16 v[16:19], v[16:19], v[110:113], v[12:15]
	v_mfma_f32_16x16x32_bf16 v[12:15], v[32:35], v[88:91], v[80:83]
	ds_read_b128 v[48:51], v103 offset:36864
	s_nop 1
	ds_read_b128 v[80:83], v103 offset:38912
	s_waitcnt vmcnt(0) lgkmcnt(0)
	s_barrier
	s_cbranch_vccnz .Lge3_exit1
	s_setprio 1
	v_mfma_f32_16x16x32_bf16 v[20:23], v[32:35], v[92:95], v[20:23]
	s_add_i32 m0, s72, 0x8000
	v_lshl_add_u64 v[246:247], s[4:5], 0, v[64:65]
	v_lshl_add_u64 v[246:247], v[246:247], 0, s[16:17]
	global_load_lds_dwordx4 v[246:247], off
	v_mfma_f32_16x16x32_bf16 v[24:27], v[32:35], v[106:109], v[24:27]
	s_add_i32 m0, s72, 0xc000
	v_lshl_add_u64 v[246:247], s[4:5], 0, v[72:73]
	v_lshl_add_u64 v[246:247], v[246:247], 0, s[18:19]
	global_load_lds_dwordx4 v[246:247], off
	v_mfma_f32_16x16x32_bf16 v[32:35], v[32:35], v[110:113], v[28:31]
	s_add_i32 m0, s72, 0x8400
	v_lshl_add_u64 v[246:247], s[4:5], 0, v[66:67]
	v_lshl_add_u64 v[246:247], v[246:247], 0, s[16:17]
	global_load_lds_dwordx4 v[246:247], off
	s_waitcnt lgkmcnt(0)
	v_mfma_f32_16x16x32_bf16 v[28:31], v[48:51], v[88:91], v[114:117]
	s_add_i32 m0, s72, 0xc400
	v_lshl_add_u64 v[246:247], s[4:5], 0, v[74:75]
	v_lshl_add_u64 v[246:247], v[246:247], 0, s[18:19]
	global_load_lds_dwordx4 v[246:247], off
	v_mfma_f32_16x16x32_bf16 v[36:39], v[48:51], v[92:95], v[36:39]
	s_add_i32 m0, s72, 0x8800
	v_lshl_add_u64 v[246:247], s[4:5], 0, v[68:69]
	v_lshl_add_u64 v[246:247], v[246:247], 0, s[16:17]
	global_load_lds_dwordx4 v[246:247], off
	v_mfma_f32_16x16x32_bf16 v[40:43], v[48:51], v[106:109], v[40:43]
	s_add_i32 m0, s72, 0xc800
	v_lshl_add_u64 v[246:247], s[4:5], 0, v[76:77]
	v_lshl_add_u64 v[246:247], v[246:247], 0, s[18:19]
	global_load_lds_dwordx4 v[246:247], off
	v_mfma_f32_16x16x32_bf16 v[48:51], v[48:51], v[110:113], v[44:47]
	s_add_i32 m0, s78, 0x8000
	v_lshl_add_u64 v[246:247], s[4:5], 0, v[70:71]
	v_lshl_add_u64 v[246:247], v[246:247], 0, s[16:17]
	global_load_lds_dwordx4 v[246:247], off
	v_mfma_f32_16x16x32_bf16 v[44:47], v[80:83], v[88:91], v[84:87]
	s_add_i32 m0, s78, 0xc000
	v_lshl_add_u64 v[246:247], s[4:5], 0, v[78:79]
	v_lshl_add_u64 v[246:247], v[246:247], 0, s[18:19]
	global_load_lds_dwordx4 v[246:247], off
	v_mfma_f32_16x16x32_bf16 v[52:55], v[80:83], v[92:95], v[52:55]
	v_mfma_f32_16x16x32_bf16 v[56:59], v[80:83], v[106:109], v[56:59]
	v_mfma_f32_16x16x32_bf16 v[60:63], v[80:83], v[110:113], v[60:63]
	s_cmpk_gt_u32 s85, 0x37f
	s_branch .Lge3_k0

; #define GBAR() do { asm volatile("s_waitcnt vmcnt(0) lgkmcnt(0)" ::: "memory"); __builtin_amdgcn_s_barrier(); } while (0)
; template <int EPI, bool GUARD>
; DEVI void gemm_tile(const Params& p, const bf16_t* __restrict__ A, int lda, const bf16_t* __restrict__ Bt, int ldb, int K,
;                           int row_base, int row_lo, int row_hi, int tile_n, int layer, int which, char* lds) {
;     ...
;   const int swz = c16 >> 1;
;   int koff[2];
; #pragma unroll
;   for (int ks = 0; ks < 2; ++ks) koff[ks] = ((ks * 4 + q4) ^ swz) << 4;
;   const int arow = (wr * 64 + c16) * 128, brow = 16384 + (wc * 64 + c16) * 128;
;     ...
;   GISSUE(0, 0); GBAR();
;   for (int k0 = 0; k0 < K; k0 += 128) {
;     GISSUE(k0 + 64, 1);
;     KSTEPS(0);
;     GBAR();
;     if (k0 + 128 < K) GISSUE(k0 + 128, 0);
;     KSTEPS(1);
;     GBAR();
;   }
.Lge3_k0:
	ds_read_b128 v[106:109], v101
	ds_read_b128 v[110:113], v102 offset:16384
	ds_read_b128 v[114:117], v101 offset:2048
	ds_read_b128 v[118:121], v102 offset:18432
	ds_read_b128 v[122:125], v102 offset:20480
	ds_read_b128 v[130:133], v102 offset:22528
	s_waitcnt lgkmcnt(0)
	v_mfma_f32_16x16x32_bf16 v[0:3], v[106:109], v[110:113], v[0:3]
	s_cselect_b64 s[52:53], -1, 0
	s_and_b64 vcc, exec, s[52:53]
	v_mfma_f32_16x16x32_bf16 v[4:7], v[106:109], v[118:121], v[4:7]
	v_mfma_f32_16x16x32_bf16 v[8:11], v[106:109], v[122:125], v[8:11]
	v_mfma_f32_16x16x32_bf16 v[16:19], v[106:109], v[130:133], v[16:19]
	s_setprio 0
	v_mfma_f32_16x16x32_bf16 v[106:109], v[114:117], v[110:113], v[12:15]
	v_mfma_f32_16x16x32_bf16 v[20:23], v[114:117], v[118:121], v[20:23]
	v_mfma_f32_16x16x32_bf16 v[24:27], v[114:117], v[122:125], v[24:27]
	v_mfma_f32_16x16x32_bf16 v[32:35], v[114:117], v[130:133], v[32:35]
	ds_read_b128 v[12:15], v101 offset:4096
	ds_read_b128 v[114:117], v101 offset:6144
	s_waitcnt lgkmcnt(0)
	v_mfma_f32_16x16x32_bf16 v[140:143], v[12:15], v[110:113], v[28:31]
	v_mfma_f32_16x16x32_bf16 v[36:39], v[12:15], v[118:121], v[36:39]
	v_mfma_f32_16x16x32_bf16 v[40:43], v[12:15], v[122:125], v[40:43]
	v_mfma_f32_16x16x32_bf16 v[48:51], v[12:15], v[130:133], v[48:51]
	ds_read_b128 v[12:15], v103
	v_mfma_f32_16x16x32_bf16 v[110:113], v[114:117], v[110:113], v[44:47]
	v_mfma_f32_16x16x32_bf16 v[52:55], v[114:117], v[118:121], v[52:55]
	v_mfma_f32_16x16x32_bf16 v[56:59], v[114:117], v[122:125], v[56:59]
	v_mfma_f32_16x16x32_bf16 v[60:63], v[114:117], v[130:133], v[60:63]
	ds_read_b128 v[114:117], v104 offset:16384
	ds_read_b128 v[28:31], v103 offset:2048
	ds_read_b128 v[118:121], v104 offset:18432
	ds_read_b128 v[122:125], v104 offset:20480
	ds_read_b128 v[130:133], v104 offset:22528
	s_waitcnt lgkmcnt(0)
	v_mfma_f32_16x16x32_bf16 v[0:3], v[12:15], v[114:117], v[0:3]
	v_mfma_f32_16x16x32_bf16 v[4:7], v[12:15], v[118:121], v[4:7]
	v_mfma_f32_16x16x32_bf16 v[8:11], v[12:15], v[122:125], v[8:11]
	v_mfma_f32_16x16x32_bf16 v[12:15], v[12:15], v[130:133], v[16:19]
	v_mfma_f32_16x16x32_bf16 v[16:19], v[28:31], v[114:117], v[106:109]
	ds_read_b128 v[44:47], v103 offset:4096
	s_nop 1
	ds_read_b128 v[106:109], v103 offset:6144
	s_waitcnt vmcnt(0) lgkmcnt(0)
	s_barrier
	s_cbranch_vccnz .Lge3_last0
	s_setprio 1
	v_mfma_f32_16x16x32_bf16 v[20:23], v[28:31], v[118:121], v[20:23]
	s_mov_b32 m0, s72
	v_lshl_add_u64 v[246:247], s[4:5], 0, v[64:65]
	v_lshl_add_u64 v[246:247], v[246:247], 0, s[26:27]
	global_load_lds_dwordx4 v[246:247], off
	v_mfma_f32_16x16x32_bf16 v[24:27], v[28:31], v[122:125], v[24:27]
	s_mov_b32 m0, s73
	v_lshl_add_u64 v[246:247], s[4:5], 0, v[72:73]
	v_lshl_add_u64 v[246:247], v[246:247], 0, s[34:35]
	global_load_lds_dwordx4 v[246:247], off
	v_mfma_f32_16x16x32_bf16 v[28:31], v[28:31], v[130:133], v[32:35]
	s_mov_b32 m0, s74
	v_lshl_add_u64 v[246:247], s[4:5], 0, v[66:67]
	v_lshl_add_u64 v[246:247], v[246:247], 0, s[26:27]
	global_load_lds_dwordx4 v[246:247], off
	s_waitcnt lgkmcnt(0)
	v_mfma_f32_16x16x32_bf16 v[32:35], v[44:47], v[114:117], v[140:143]
	s_mov_b32 m0, s75
	v_lshl_add_u64 v[246:247], s[4:5], 0, v[74:75]
	v_lshl_add_u64 v[246:247], v[246:247], 0, s[34:35]
	global_load_lds_dwordx4 v[246:247], off
	v_mfma_f32_16x16x32_bf16 v[36:39], v[44:47], v[118:121], v[36:39]
	s_mov_b32 m0, s76
	v_lshl_add_u64 v[246:247], s[4:5], 0, v[68:69]
	v_lshl_add_u64 v[246:247], v[246:247], 0, s[26:27]
	global_load_lds_dwordx4 v[246:247], off
	v_mfma_f32_16x16x32_bf16 v[40:43], v[44:47], v[122:125], v[40:43]
	s_mov_b32 m0, s77
	v_lshl_add_u64 v[246:247], s[4:5], 0, v[76:77]
	v_lshl_add_u64 v[246:247], v[246:247], 0, s[34:35]
	global_load_lds_dwordx4 v[246:247], off
	v_mfma_f32_16x16x32_bf16 v[44:47], v[44:47], v[130:133], v[48:51]
	s_mov_b32 m0, s78
	v_lshl_add_u64 v[246:247], s[4:5], 0, v[70:71]
	v_lshl_add_u64 v[246:247], v[246:247], 0, s[26:27]
	global_load_lds_dwordx4 v[246:247], off
	v_mfma_f32_16x16x32_bf16 v[48:51], v[106:109], v[114:117], v[110:113]
	s_mov_b32 m0, s79
	v_lshl_add_u64 v[246:247], s[4:5], 0, v[78:79]
	v_lshl_add_u64 v[246:247], v[246:247], 0, s[34:35]
	global_load_lds_dwordx4 v[246:247], off
	v_mfma_f32_16x16x32_bf16 v[52:55], v[106:109], v[118:121], v[52:55]
	v_mfma_f32_16x16x32_bf16 v[56:59], v[106:109], v[122:125], v[56:59]
	v_mfma_f32_16x16x32_bf16 v[60:63], v[106:109], v[130:133], v[60:63]
	s_branch .LBB0_878

; #define GBAR() do { asm volatile("s_waitcnt vmcnt(0) lgkmcnt(0)" ::: "memory"); __builtin_amdgcn_s_barrier(); } while (0)
; template <int EPI, bool GUARD>
; DEVI void gemm_tile(const Params& p, const bf16_t* __restrict__ A, int lda, const bf16_t* __restrict__ Bt, int ldb, int K,
;                           int row_base, int row_lo, int row_hi, int tile_n, int layer, int which, char* lds) {
;     ...
;   const int swz = c16 >> 1;
;   int koff[2];
; #pragma unroll
;   for (int ks = 0; ks < 2; ++ks) koff[ks] = ((ks * 4 + q4) ^ swz) << 4;
;   const int arow = (wr * 64 + c16) * 128, brow = 16384 + (wc * 64 + c16) * 128;
;     ...
;   GISSUE(0, 0); GBAR();
;   for (int k0 = 0; k0 < K; k0 += 128) {
;     GISSUE(k0 + 64, 1);
;     KSTEPS(0);
;     GBAR();
;     if (k0 + 128 < K) GISSUE(k0 + 128, 0);
;     KSTEPS(1);
;     GBAR();
;   }
.LBB0_959:
	ds_read_b128 v[82:85], v64 offset:32768
	ds_read_b128 v[86:89], v103 offset:49152
	ds_read_b128 v[90:93], v64 offset:34816
	ds_read_b128 v[94:97], v103 offset:51200
	ds_read_b128 v[106:109], v103 offset:53248
	ds_read_b128 v[110:113], v103 offset:55296
	s_addk_i32 s69, 0x80
	s_waitcnt lgkmcnt(0)
	v_mfma_f32_16x16x32_bf16 v[0:3], v[82:85], v[86:89], v[0:3]
	s_add_u32 s34, s34, 0x100
	s_addc_u32 s35, s35, 0
	s_and_b64 vcc, exec, s[44:45]
	v_mfma_f32_16x16x32_bf16 v[4:7], v[82:85], v[94:97], v[4:7]
	v_mfma_f32_16x16x32_bf16 v[8:11], v[82:85], v[106:109], v[8:11]
	v_mfma_f32_16x16x32_bf16 v[82:85], v[82:85], v[110:113], v[12:15]
	s_setprio 0
	v_mfma_f32_16x16x32_bf16 v[16:19], v[90:93], v[86:89], v[16:19]
	v_mfma_f32_16x16x32_bf16 v[20:23], v[90:93], v[94:97], v[20:23]
	v_mfma_f32_16x16x32_bf16 v[24:27], v[90:93], v[106:109], v[24:27]
	v_mfma_f32_16x16x32_bf16 v[28:31], v[90:93], v[110:113], v[28:31]
	ds_read_b128 v[12:15], v64 offset:36864
	ds_read_b128 v[90:93], v64 offset:38912
	s_waitcnt lgkmcnt(0)
	v_mfma_f32_16x16x32_bf16 v[114:117], v[12:15], v[94:97], v[36:39]
	v_mfma_f32_16x16x32_bf16 v[52:55], v[90:93], v[94:97], v[52:55]
	ds_read_b128 v[94:97], v104 offset:32768
	v_mfma_f32_16x16x32_bf16 v[32:35], v[12:15], v[86:89], v[32:35]
	v_mfma_f32_16x16x32_bf16 v[40:43], v[12:15], v[106:109], v[40:43]
	v_mfma_f32_16x16x32_bf16 v[44:47], v[12:15], v[110:113], v[44:47]
	v_mfma_f32_16x16x32_bf16 v[86:89], v[90:93], v[86:89], v[48:51]
	v_mfma_f32_16x16x32_bf16 v[56:59], v[90:93], v[106:109], v[56:59]
	v_mfma_f32_16x16x32_bf16 v[60:63], v[90:93], v[110:113], v[60:63]
	ds_read_b128 v[90:93], v105 offset:49152
	ds_read_b128 v[106:109], v104 offset:34816
	ds_read_b128 v[110:113], v105 offset:51200
	ds_read_b128 v[118:121], v105 offset:53248
	ds_read_b128 v[128:131], v105 offset:55296
	s_waitcnt lgkmcnt(0)
	v_mfma_f32_16x16x32_bf16 v[48:51], v[94:97], v[90:93], v[0:3]
	v_mfma_f32_16x16x32_bf16 v[36:39], v[94:97], v[110:113], v[4:7]
	v_mfma_f32_16x16x32_bf16 v[12:15], v[94:97], v[118:121], v[8:11]
	v_mfma_f32_16x16x32_bf16 v[8:11], v[94:97], v[128:131], v[82:85]
	s_nop 2
	ds_read_b128 v[82:85], v104 offset:36864
	ds_read_b128 v[94:97], v104 offset:38912
	s_waitcnt vmcnt(0) lgkmcnt(0)
	s_barrier
	s_cbranch_vccnz .Lge4_exit1
	s_setprio 1
	v_mfma_f32_16x16x32_bf16 v[4:7], v[106:109], v[90:93], v[16:19]
	s_add_i32 m0, s59, 0x8000
	v_lshl_add_u64 v[246:247], s[34:35], 0, v[66:67]
	v_lshl_add_u64 v[246:247], v[246:247], 0, s[4:5]
	global_load_lds_dwordx4 v[246:247], off
	v_mfma_f32_16x16x32_bf16 v[0:3], v[106:109], v[110:113], v[20:23]
	s_add_i32 m0, s59, 0xc000
	v_lshl_add_u64 v[246:247], s[34:35], 0, v[74:75]
	v_lshl_add_u64 v[246:247], v[246:247], 0, s[16:17]
	global_load_lds_dwordx4 v[246:247], off
	v_mfma_f32_16x16x32_bf16 v[16:19], v[106:109], v[118:121], v[24:27]
	s_add_i32 m0, s59, 0x8400
	v_lshl_add_u64 v[246:247], s[34:35], 0, v[68:69]
	v_lshl_add_u64 v[246:247], v[246:247], 0, s[4:5]
	global_load_lds_dwordx4 v[246:247], off
	v_mfma_f32_16x16x32_bf16 v[24:27], v[106:109], v[128:131], v[28:31]
	s_add_i32 m0, s59, 0xc400
	v_lshl_add_u64 v[246:247], s[34:35], 0, v[76:77]
	v_lshl_add_u64 v[246:247], v[246:247], 0, s[16:17]
	global_load_lds_dwordx4 v[246:247], off
	s_waitcnt lgkmcnt(0)
	v_mfma_f32_16x16x32_bf16 v[20:23], v[82:85], v[90:93], v[32:35]
	s_add_i32 m0, s59, 0x8800
	v_lshl_add_u64 v[246:247], s[34:35], 0, v[70:71]
	v_lshl_add_u64 v[246:247], v[246:247], 0, s[4:5]
	global_load_lds_dwordx4 v[246:247], off
	v_mfma_f32_16x16x32_bf16 v[28:31], v[82:85], v[110:113], v[114:117]
	s_add_i32 m0, s59, 0xc800
	v_lshl_add_u64 v[246:247], s[34:35], 0, v[78:79]
	v_lshl_add_u64 v[246:247], v[246:247], 0, s[16:17]
	global_load_lds_dwordx4 v[246:247], off
	v_mfma_f32_16x16x32_bf16 v[32:35], v[82:85], v[118:121], v[40:43]
	s_add_i32 m0, s65, 0x8000
	v_lshl_add_u64 v[246:247], s[34:35], 0, v[72:73]
	v_lshl_add_u64 v[246:247], v[246:247], 0, s[4:5]
	global_load_lds_dwordx4 v[246:247], off
	v_mfma_f32_16x16x32_bf16 v[44:47], v[82:85], v[128:131], v[44:47]
	s_add_i32 m0, s65, 0xc000
	v_lshl_add_u64 v[246:247], s[34:35], 0, v[80:81]
	v_lshl_add_u64 v[246:247], v[246:247], 0, s[16:17]
	global_load_lds_dwordx4 v[246:247], off
	v_mfma_f32_16x16x32_bf16 v[40:43], v[94:97], v[90:93], v[86:89]
	v_mfma_f32_16x16x32_bf16 v[52:55], v[94:97], v[110:113], v[52:55]
	v_mfma_f32_16x16x32_bf16 v[56:59], v[94:97], v[118:121], v[56:59]
	v_mfma_f32_16x16x32_bf16 v[60:63], v[94:97], v[128:131], v[60:63]
	s_cmpk_gt_u32 s69, 0x27f
	s_branch .Lge4_k0

; #define GBAR() do { asm volatile("s_waitcnt vmcnt(0) lgkmcnt(0)" ::: "memory"); __builtin_amdgcn_s_barrier(); } while (0)
; template <int EPI, bool GUARD>
; DEVI void gemm_tile(const Params& p, const bf16_t* __restrict__ A, int lda, const bf16_t* __restrict__ Bt, int ldb, int K,
;                           int row_base, int row_lo, int row_hi, int tile_n, int layer, int which, char* lds) {
;     ...
;   const int swz = c16 >> 1;
;   int koff[2];
; #pragma unroll
;   for (int ks = 0; ks < 2; ++ks) koff[ks] = ((ks * 4 + q4) ^ swz) << 4;
;   const int arow = (wr * 64 + c16) * 128, brow = 16384 + (wc * 64 + c16) * 128;
;     ...
;   GISSUE(0, 0); GBAR();
;   for (int k0 = 0; k0 < K; k0 += 128) {
;     GISSUE(k0 + 64, 1);
;     KSTEPS(0);
;     GBAR();
;     if (k0 + 128 < K) GISSUE(k0 + 128, 0);
;     KSTEPS(1);
;     GBAR();
;   }
.Lge4_k0:
	ds_read_b128 v[106:109], v64
	ds_read_b128 v[110:113], v103 offset:16384
	ds_read_b128 v[114:117], v64 offset:2048
	ds_read_b128 v[118:121], v103 offset:18432
	ds_read_b128 v[128:131], v103 offset:20480
	ds_read_b128 v[136:139], v103 offset:22528
	s_waitcnt lgkmcnt(0)
	v_mfma_f32_16x16x32_bf16 v[140:143], v[114:117], v[110:113], v[4:7]
	s_cselect_b64 s[44:45], -1, 0
	s_and_b64 vcc, exec, s[44:45]
	v_mfma_f32_16x16x32_bf16 v[144:147], v[114:117], v[118:121], v[0:3]
	s_nop 2
	ds_read_b128 v[0:3], v64 offset:4096
	ds_read_b128 v[4:7], v64 offset:6144
	v_mfma_f32_16x16x32_bf16 v[148:151], v[114:117], v[128:131], v[16:19]
	s_nop 2
	ds_read_b128 v[16:19], v104
	v_mfma_f32_16x16x32_bf16 v[48:51], v[106:109], v[110:113], v[48:51]
	s_setprio 0
	v_mfma_f32_16x16x32_bf16 v[36:39], v[106:109], v[118:121], v[36:39]
	v_mfma_f32_16x16x32_bf16 v[12:15], v[106:109], v[128:131], v[12:15]
	v_mfma_f32_16x16x32_bf16 v[106:109], v[106:109], v[136:139], v[8:11]
	v_mfma_f32_16x16x32_bf16 v[114:117], v[114:117], v[136:139], v[24:27]
	s_waitcnt lgkmcnt(0)
	v_mfma_f32_16x16x32_bf16 v[156:159], v[0:3], v[118:121], v[28:31]
	v_mfma_f32_16x16x32_bf16 v[160:163], v[0:3], v[128:131], v[32:35]
	v_mfma_f32_16x16x32_bf16 v[44:47], v[0:3], v[136:139], v[44:47]
	v_mfma_f32_16x16x32_bf16 v[52:55], v[4:7], v[118:121], v[52:55]
	v_mfma_f32_16x16x32_bf16 v[56:59], v[4:7], v[128:131], v[56:59]
	ds_read_b128 v[118:121], v105 offset:16384
	ds_read_b128 v[28:31], v104 offset:2048
	ds_read_b128 v[128:131], v105 offset:18432
	v_mfma_f32_16x16x32_bf16 v[60:63], v[4:7], v[136:139], v[60:63]
	ds_read_b128 v[136:139], v105 offset:20480
	ds_read_b128 v[166:169], v105 offset:22528
	v_mfma_f32_16x16x32_bf16 v[152:155], v[0:3], v[110:113], v[20:23]
	s_waitcnt lgkmcnt(0)
	v_mfma_f32_16x16x32_bf16 v[0:3], v[16:19], v[118:121], v[48:51]
	v_mfma_f32_16x16x32_bf16 v[8:11], v[16:19], v[136:139], v[12:15]
	v_mfma_f32_16x16x32_bf16 v[12:15], v[16:19], v[166:169], v[106:109]
	s_nop 0
	ds_read_b128 v[48:51], v104 offset:4096
	s_nop 0
	ds_read_b128 v[106:109], v104 offset:6144
	s_waitcnt vmcnt(0) lgkmcnt(0)
	s_barrier
	s_cbranch_vccnz .Lge4_last0
	s_setprio 1
	v_mfma_f32_16x16x32_bf16 v[110:113], v[4:7], v[110:113], v[40:43]
	s_mov_b32 m0, s59
	v_lshl_add_u64 v[246:247], s[34:35], 0, v[66:67]
	v_lshl_add_u64 v[246:247], v[246:247], 0, s[18:19]
	global_load_lds_dwordx4 v[246:247], off
	v_mfma_f32_16x16x32_bf16 v[4:7], v[16:19], v[128:131], v[36:39]
	s_mov_b32 m0, s60
	v_lshl_add_u64 v[246:247], s[34:35], 0, v[74:75]
	v_lshl_add_u64 v[246:247], v[246:247], 0, s[26:27]
	global_load_lds_dwordx4 v[246:247], off
	v_mfma_f32_16x16x32_bf16 v[16:19], v[28:31], v[118:121], v[140:143]
	s_mov_b32 m0, s61
	v_lshl_add_u64 v[246:247], s[34:35], 0, v[68:69]
	v_lshl_add_u64 v[246:247], v[246:247], 0, s[18:19]
	global_load_lds_dwordx4 v[246:247], off
	v_mfma_f32_16x16x32_bf16 v[20:23], v[28:31], v[128:131], v[144:147]
	s_mov_b32 m0, s62
	v_lshl_add_u64 v[246:247], s[34:35], 0, v[76:77]
	v_lshl_add_u64 v[246:247], v[246:247], 0, s[26:27]
	global_load_lds_dwordx4 v[246:247], off
	v_mfma_f32_16x16x32_bf16 v[24:27], v[28:31], v[136:139], v[148:151]
	s_mov_b32 m0, s63
	v_lshl_add_u64 v[246:247], s[34:35], 0, v[70:71]
	v_lshl_add_u64 v[246:247], v[246:247], 0, s[18:19]
	global_load_lds_dwordx4 v[246:247], off
	v_mfma_f32_16x16x32_bf16 v[28:31], v[28:31], v[166:169], v[114:117]
	s_mov_b32 m0, s64
	v_lshl_add_u64 v[246:247], s[34:35], 0, v[78:79]
	v_lshl_add_u64 v[246:247], v[246:247], 0, s[26:27]
	global_load_lds_dwordx4 v[246:247], off
	s_waitcnt lgkmcnt(0)
	v_mfma_f32_16x16x32_bf16 v[32:35], v[48:51], v[118:121], v[152:155]
	s_mov_b32 m0, s65
	v_lshl_add_u64 v[246:247], s[34:35], 0, v[72:73]
	v_lshl_add_u64 v[246:247], v[246:247], 0, s[18:19]
	global_load_lds_dwordx4 v[246:247], off
	v_mfma_f32_16x16x32_bf16 v[36:39], v[48:51], v[128:131], v[156:159]
	s_mov_b32 m0, s68
	v_lshl_add_u64 v[246:247], s[34:35], 0, v[80:81]
	v_lshl_add_u64 v[246:247], v[246:247], 0, s[26:27]
	global_load_lds_dwordx4 v[246:247], off
	v_mfma_f32_16x16x32_bf16 v[40:43], v[48:51], v[136:139], v[160:163]
	v_mfma_f32_16x16x32_bf16 v[44:47], v[48:51], v[166:169], v[44:47]
	v_mfma_f32_16x16x32_bf16 v[48:51], v[106:109], v[118:121], v[110:113]
	v_mfma_f32_16x16x32_bf16 v[52:55], v[106:109], v[128:131], v[52:55]
	v_mfma_f32_16x16x32_bf16 v[56:59], v[106:109], v[136:139], v[56:59]
	v_mfma_f32_16x16x32_bf16 v[60:63], v[106:109], v[166:169], v[60:63]
	s_branch .LBB0_959

; #define GBAR() do { asm volatile("s_waitcnt vmcnt(0) lgkmcnt(0)" ::: "memory"); __builtin_amdgcn_s_barrier(); } while (0)
; template <int EPI, bool GUARD>
; DEVI void gemm_tile(const Params& p, const bf16_t* __restrict__ A, int lda, const bf16_t* __restrict__ Bt, int ldb, int K,
;                           int row_base, int row_lo, int row_hi, int tile_n, int layer, int which, char* lds) {
;     ...
;   const int swz = c16 >> 1;
;   int koff[2];
; #pragma unroll
;   for (int ks = 0; ks < 2; ++ks) koff[ks] = ((ks * 4 + q4) ^ swz) << 4;
;   const int arow = (wr * 64 + c16) * 128, brow = 16384 + (wc * 64 + c16) * 128;
;     ...
;   GISSUE(0, 0); GBAR();
;   for (int k0 = 0; k0 < K; k0 += 128) {
;     GISSUE(k0 + 64, 1);
;     KSTEPS(0);
;     GBAR();
;     if (k0 + 128 < K) GISSUE(k0 + 128, 0);
;     KSTEPS(1);
;     GBAR();
;   }
.LBB0_1131:
	ds_read_b128 v[82:85], v64 offset:32768
	ds_read_b128 v[86:89], v107 offset:49152
	ds_read_b128 v[90:93], v64 offset:34816
	ds_read_b128 v[94:97], v107 offset:51200
	ds_read_b128 v[110:113], v107 offset:53248
	ds_read_b128 v[114:117], v107 offset:55296
	s_addk_i32 s52, 0x80
	s_waitcnt lgkmcnt(0)
	v_mfma_f32_16x16x32_bf16 v[0:3], v[82:85], v[86:89], v[0:3]
	s_add_u32 s18, s18, 0x100
	s_addc_u32 s19, s19, 0
	s_andn2_b64 vcc, exec, s[26:27]
	v_mfma_f32_16x16x32_bf16 v[4:7], v[82:85], v[94:97], v[4:7]
	v_mfma_f32_16x16x32_bf16 v[8:11], v[82:85], v[110:113], v[8:11]
	v_mfma_f32_16x16x32_bf16 v[12:15], v[82:85], v[114:117], v[12:15]
	s_setprio 0
	v_mfma_f32_16x16x32_bf16 v[16:19], v[90:93], v[86:89], v[16:19]
	v_mfma_f32_16x16x32_bf16 v[20:23], v[90:93], v[94:97], v[20:23]
	v_mfma_f32_16x16x32_bf16 v[24:27], v[90:93], v[110:113], v[24:27]
	v_mfma_f32_16x16x32_bf16 v[28:31], v[90:93], v[114:117], v[28:31]
	ds_read_b128 v[82:85], v64 offset:36864
	ds_read_b128 v[90:93], v64 offset:38912
	s_waitcnt lgkmcnt(0)
	v_mfma_f32_16x16x32_bf16 v[118:121], v[82:85], v[86:89], v[32:35]
	s_nop 2
	ds_read_b128 v[32:35], v108 offset:32768
	v_mfma_f32_16x16x32_bf16 v[122:125], v[82:85], v[94:97], v[36:39]
	v_mfma_f32_16x16x32_bf16 v[126:129], v[82:85], v[110:113], v[40:43]
	v_mfma_f32_16x16x32_bf16 v[82:85], v[82:85], v[114:117], v[44:47]
	v_mfma_f32_16x16x32_bf16 v[86:89], v[90:93], v[86:89], v[48:51]
	v_mfma_f32_16x16x32_bf16 v[94:97], v[90:93], v[94:97], v[52:55]
	v_mfma_f32_16x16x32_bf16 v[110:113], v[90:93], v[110:113], v[56:59]
	v_mfma_f32_16x16x32_bf16 v[90:93], v[90:93], v[114:117], v[60:63]
	ds_read_b128 v[114:117], v109 offset:49152
	ds_read_b128 v[130:133], v108 offset:34816
	ds_read_b128 v[134:137], v109 offset:51200
	ds_read_b128 v[138:141], v109 offset:53248
	ds_read_b128 v[142:145], v109 offset:55296
	s_waitcnt lgkmcnt(0)
	v_mfma_f32_16x16x32_bf16 v[60:63], v[32:35], v[114:117], v[0:3]
	v_mfma_f32_16x16x32_bf16 v[52:55], v[32:35], v[138:141], v[8:11]
	s_nop 1
	ds_read_b128 v[0:3], v108 offset:36864
	ds_read_b128 v[8:11], v108 offset:38912
	s_waitcnt vmcnt(0) lgkmcnt(0)
	s_barrier
	s_cbranch_vccz .Lge5_exit1
	s_setprio 1
	v_mfma_f32_16x16x32_bf16 v[56:59], v[32:35], v[134:137], v[4:7]
	s_mov_b32 m0, s53
	v_lshl_add_u64 v[246:247], s[18:19], 0, v[66:67]
	v_lshl_add_u64 v[246:247], v[246:247], 0, s[2:3]
	global_load_lds_dwordx4 v[246:247], off
	v_mfma_f32_16x16x32_bf16 v[48:51], v[32:35], v[142:145], v[12:15]
	s_mov_b32 m0, s57
	v_lshl_add_u64 v[246:247], s[18:19], 0, v[74:75]
	v_lshl_add_u64 v[246:247], v[246:247], 0, s[4:5]
	global_load_lds_dwordx4 v[246:247], off
	v_mfma_f32_16x16x32_bf16 v[44:47], v[130:133], v[114:117], v[16:19]
	s_mov_b32 m0, s54
	v_lshl_add_u64 v[246:247], s[18:19], 0, v[68:69]
	v_lshl_add_u64 v[246:247], v[246:247], 0, s[2:3]
	global_load_lds_dwordx4 v[246:247], off
	v_mfma_f32_16x16x32_bf16 v[40:43], v[130:133], v[134:137], v[20:23]
	s_mov_b32 m0, s55
	v_lshl_add_u64 v[246:247], s[18:19], 0, v[76:77]
	v_lshl_add_u64 v[246:247], v[246:247], 0, s[4:5]
	global_load_lds_dwordx4 v[246:247], off
	v_mfma_f32_16x16x32_bf16 v[36:39], v[130:133], v[138:141], v[24:27]
	s_mov_b32 m0, s58
	v_lshl_add_u64 v[246:247], s[18:19], 0, v[70:71]
	v_lshl_add_u64 v[246:247], v[246:247], 0, s[2:3]
	global_load_lds_dwordx4 v[246:247], off
	v_mfma_f32_16x16x32_bf16 v[32:35], v[130:133], v[142:145], v[28:31]
	s_mov_b32 m0, s56
	v_lshl_add_u64 v[246:247], s[18:19], 0, v[78:79]
	v_lshl_add_u64 v[246:247], v[246:247], 0, s[4:5]
	global_load_lds_dwordx4 v[246:247], off
	s_waitcnt lgkmcnt(0)
	v_mfma_f32_16x16x32_bf16 v[28:31], v[0:3], v[114:117], v[118:121]
	s_mov_b32 m0, s59
	v_lshl_add_u64 v[246:247], s[18:19], 0, v[72:73]
	v_lshl_add_u64 v[246:247], v[246:247], 0, s[2:3]
	global_load_lds_dwordx4 v[246:247], off
	v_mfma_f32_16x16x32_bf16 v[24:27], v[0:3], v[134:137], v[122:125]
	s_mov_b32 m0, s60
	v_lshl_add_u64 v[246:247], s[18:19], 0, v[80:81]
	v_lshl_add_u64 v[246:247], v[246:247], 0, s[4:5]
	global_load_lds_dwordx4 v[246:247], off
	v_mfma_f32_16x16x32_bf16 v[16:19], v[0:3], v[138:141], v[126:129]
	v_mfma_f32_16x16x32_bf16 v[12:15], v[0:3], v[142:145], v[82:85]
	v_mfma_f32_16x16x32_bf16 v[4:7], v[8:11], v[114:117], v[86:89]
	v_mfma_f32_16x16x32_bf16 v[0:3], v[8:11], v[134:137], v[94:97]
	v_mfma_f32_16x16x32_bf16 v[20:23], v[8:11], v[138:141], v[110:113]
	v_mfma_f32_16x16x32_bf16 v[8:11], v[8:11], v[142:145], v[90:93]
	s_cmpk_gt_u32 s52, 0x37f
	s_cselect_b64 s[26:27], -1, 0
	s_and_b64 vcc, exec, s[26:27]
	s_branch .Lge5_k0

; #define GBAR() do { asm volatile("s_waitcnt vmcnt(0) lgkmcnt(0)" ::: "memory"); __builtin_amdgcn_s_barrier(); } while (0)
; template <int EPI, bool GUARD>
; DEVI void gemm_tile(const Params& p, const bf16_t* __restrict__ A, int lda, const bf16_t* __restrict__ Bt, int ldb, int K,
;                           int row_base, int row_lo, int row_hi, int tile_n, int layer, int which, char* lds) {
;     ...
;   const int swz = c16 >> 1;
;   int koff[2];
; #pragma unroll
;   for (int ks = 0; ks < 2; ++ks) koff[ks] = ((ks * 4 + q4) ^ swz) << 4;
;   const int arow = (wr * 64 + c16) * 128, brow = 16384 + (wc * 64 + c16) * 128;
;     ...
;   GISSUE(0, 0); GBAR();
;   for (int k0 = 0; k0 < K; k0 += 128) {
;     GISSUE(k0 + 64, 1);
;     KSTEPS(0);
;     GBAR();
;     if (k0 + 128 < K) GISSUE(k0 + 128, 0);
;     KSTEPS(1);
;     GBAR();
;   }
.Lge5_k0:
	ds_read_b128 v[110:113], v64
	ds_read_b128 v[114:117], v107 offset:16384
	ds_read_b128 v[118:121], v64 offset:2048
	ds_read_b128 v[122:125], v107 offset:18432
	ds_read_b128 v[126:129], v107 offset:20480
	ds_read_b128 v[130:133], v107 offset:22528
	s_waitcnt lgkmcnt(0)
	v_mfma_f32_16x16x32_bf16 v[60:63], v[110:113], v[114:117], v[60:63]
	v_mfma_f32_16x16x32_bf16 v[56:59], v[110:113], v[122:125], v[56:59]
	v_mfma_f32_16x16x32_bf16 v[52:55], v[110:113], v[126:129], v[52:55]
	v_mfma_f32_16x16x32_bf16 v[48:51], v[110:113], v[130:133], v[48:51]
	s_setprio 0
	v_mfma_f32_16x16x32_bf16 v[44:47], v[118:121], v[114:117], v[44:47]
	v_mfma_f32_16x16x32_bf16 v[40:43], v[118:121], v[122:125], v[40:43]
	v_mfma_f32_16x16x32_bf16 v[36:39], v[118:121], v[126:129], v[36:39]
	v_mfma_f32_16x16x32_bf16 v[32:35], v[118:121], v[130:133], v[32:35]
	ds_read_b128 v[110:113], v64 offset:4096
	ds_read_b128 v[118:121], v64 offset:6144
	s_waitcnt lgkmcnt(0)
	v_mfma_f32_16x16x32_bf16 v[134:137], v[110:113], v[114:117], v[28:31]
	v_mfma_f32_16x16x32_bf16 v[138:141], v[110:113], v[122:125], v[24:27]
	v_mfma_f32_16x16x32_bf16 v[142:145], v[110:113], v[126:129], v[16:19]
	v_mfma_f32_16x16x32_bf16 v[110:113], v[110:113], v[130:133], v[12:15]
	s_nop 2
	ds_read_b128 v[12:15], v108
	v_mfma_f32_16x16x32_bf16 v[114:117], v[118:121], v[114:117], v[4:7]
	v_mfma_f32_16x16x32_bf16 v[122:125], v[118:121], v[122:125], v[0:3]
	v_mfma_f32_16x16x32_bf16 v[126:129], v[118:121], v[126:129], v[20:23]
	v_mfma_f32_16x16x32_bf16 v[118:121], v[118:121], v[130:133], v[8:11]
	ds_read_b128 v[130:133], v109 offset:16384
	ds_read_b128 v[28:31], v108 offset:2048
	ds_read_b128 v[146:149], v109 offset:18432
	s_waitcnt lgkmcnt(0)
	v_mfma_f32_16x16x32_bf16 v[0:3], v[12:15], v[130:133], v[60:63]
	v_mfma_f32_16x16x32_bf16 v[4:7], v[12:15], v[146:149], v[56:59]
	s_nop 2
	ds_read_b128 v[56:59], v109 offset:20480
	ds_read_b128 v[60:63], v109 offset:22528
	v_mfma_f32_16x16x32_bf16 v[16:19], v[28:31], v[130:133], v[44:47]
	s_nop 2
	ds_read_b128 v[44:47], v108 offset:4096
	ds_read_b128 v[150:153], v108 offset:6144
	s_waitcnt vmcnt(0) lgkmcnt(0)
	s_barrier
	s_cbranch_vccnz .Lge5_last0
	s_setprio 1
	s_waitcnt lgkmcnt(0)
	v_mfma_f32_16x16x32_bf16 v[8:11], v[12:15], v[56:59], v[52:55]
	s_mov_b32 m0, s40
	v_lshl_add_u64 v[246:247], s[18:19], 0, v[66:67]
	v_lshl_add_u64 v[246:247], v[246:247], 0, s[6:7]
	global_load_lds_dwordx4 v[246:247], off
	v_mfma_f32_16x16x32_bf16 v[12:15], v[12:15], v[60:63], v[48:51]
	s_mov_b32 m0, s41
	v_lshl_add_u64 v[246:247], s[18:19], 0, v[74:75]
	v_lshl_add_u64 v[246:247], v[246:247], 0, s[8:9]
	global_load_lds_dwordx4 v[246:247], off
	v_mfma_f32_16x16x32_bf16 v[20:23], v[28:31], v[146:149], v[40:43]
	s_mov_b32 m0, s42
	v_lshl_add_u64 v[246:247], s[18:19], 0, v[68:69]
	v_lshl_add_u64 v[246:247], v[246:247], 0, s[6:7]
	global_load_lds_dwordx4 v[246:247], off
	v_mfma_f32_16x16x32_bf16 v[24:27], v[28:31], v[56:59], v[36:39]
	s_mov_b32 m0, s43
	v_lshl_add_u64 v[246:247], s[18:19], 0, v[76:77]
	v_lshl_add_u64 v[246:247], v[246:247], 0, s[8:9]
	global_load_lds_dwordx4 v[246:247], off
	v_mfma_f32_16x16x32_bf16 v[28:31], v[28:31], v[60:63], v[32:35]
	s_mov_b32 m0, s44
	v_lshl_add_u64 v[246:247], s[18:19], 0, v[70:71]
	v_lshl_add_u64 v[246:247], v[246:247], 0, s[6:7]
	global_load_lds_dwordx4 v[246:247], off
	v_mfma_f32_16x16x32_bf16 v[32:35], v[44:47], v[130:133], v[134:137]
	s_mov_b32 m0, s45
	v_lshl_add_u64 v[246:247], s[18:19], 0, v[78:79]
	v_lshl_add_u64 v[246:247], v[246:247], 0, s[8:9]
	global_load_lds_dwordx4 v[246:247], off
	v_mfma_f32_16x16x32_bf16 v[36:39], v[44:47], v[146:149], v[138:141]
	s_mov_b32 m0, s46
	v_lshl_add_u64 v[246:247], s[18:19], 0, v[72:73]
	v_lshl_add_u64 v[246:247], v[246:247], 0, s[6:7]
	global_load_lds_dwordx4 v[246:247], off
	v_mfma_f32_16x16x32_bf16 v[40:43], v[44:47], v[56:59], v[142:145]
	s_mov_b32 m0, s47
	v_lshl_add_u64 v[246:247], s[18:19], 0, v[80:81]
	v_lshl_add_u64 v[246:247], v[246:247], 0, s[8:9]
	global_load_lds_dwordx4 v[246:247], off
	v_mfma_f32_16x16x32_bf16 v[44:47], v[44:47], v[60:63], v[110:113]
	v_mfma_f32_16x16x32_bf16 v[48:51], v[150:153], v[130:133], v[114:117]
	v_mfma_f32_16x16x32_bf16 v[52:55], v[150:153], v[146:149], v[122:125]
	v_mfma_f32_16x16x32_bf16 v[56:59], v[150:153], v[56:59], v[126:129]
	v_mfma_f32_16x16x32_bf16 v[60:63], v[150:153], v[60:63], v[118:121]
	s_branch .LBB0_1131

; #define GBAR() do { asm volatile("s_waitcnt vmcnt(0) lgkmcnt(0)" ::: "memory"); __builtin_amdgcn_s_barrier(); } while (0)
; template <int EPI, bool GUARD>
; DEVI void gemm_tile(const Params& p, const bf16_t* __restrict__ A, int lda, const bf16_t* __restrict__ Bt, int ldb, int K,
;                           int row_base, int row_lo, int row_hi, int tile_n, int layer, int which, char* lds) {
;     ...
;   const int swz = c16 >> 1;
;   int koff[2];
; #pragma unroll
;   for (int ks = 0; ks < 2; ++ks) koff[ks] = ((ks * 4 + q4) ^ swz) << 4;
;   const int arow = (wr * 64 + c16) * 128, brow = 16384 + (wc * 64 + c16) * 128;
;     ...
;   GISSUE(0, 0); GBAR();
;   for (int k0 = 0; k0 < K; k0 += 128) {
;     GISSUE(k0 + 64, 1);
;     KSTEPS(0);
;     GBAR();
;     if (k0 + 128 < K) GISSUE(k0 + 128, 0);
;     KSTEPS(1);
;     GBAR();
;   }
.LBB0_1258:
	ds_read_b128 v[82:85], v64 offset:32768
	ds_read_b128 v[86:89], v112 offset:49152
	ds_read_b128 v[90:93], v64 offset:34816
	ds_read_b128 v[94:97], v112 offset:51200
	ds_read_b128 v[116:119], v112 offset:53248
	ds_read_b128 v[120:123], v112 offset:55296
	s_addk_i32 s51, 0x80
	s_waitcnt lgkmcnt(0)
	v_mfma_f32_16x16x32_bf16 v[0:3], v[82:85], v[86:89], v[0:3]
	s_add_u32 s2, s2, 0x100
	s_addc_u32 s3, s3, 0
	s_and_b64 vcc, exec, s[4:5]
	v_mfma_f32_16x16x32_bf16 v[4:7], v[82:85], v[94:97], v[4:7]
	v_mfma_f32_16x16x32_bf16 v[8:11], v[82:85], v[116:119], v[8:11]
	v_mfma_f32_16x16x32_bf16 v[12:15], v[82:85], v[120:123], v[12:15]
	s_setprio 0
	v_mfma_f32_16x16x32_bf16 v[82:85], v[90:93], v[86:89], v[16:19]
	v_mfma_f32_16x16x32_bf16 v[20:23], v[90:93], v[94:97], v[20:23]
	v_mfma_f32_16x16x32_bf16 v[24:27], v[90:93], v[116:119], v[24:27]
	v_mfma_f32_16x16x32_bf16 v[28:31], v[90:93], v[120:123], v[28:31]
	ds_read_b128 v[16:19], v64 offset:36864
	ds_read_b128 v[90:93], v64 offset:38912
	s_waitcnt lgkmcnt(0)
	v_mfma_f32_16x16x32_bf16 v[124:127], v[16:19], v[86:89], v[32:35]
	v_mfma_f32_16x16x32_bf16 v[36:39], v[16:19], v[94:97], v[36:39]
	v_mfma_f32_16x16x32_bf16 v[40:43], v[16:19], v[116:119], v[40:43]
	v_mfma_f32_16x16x32_bf16 v[44:47], v[16:19], v[120:123], v[44:47]
	ds_read_b128 v[16:19], v113 offset:32768
	v_mfma_f32_16x16x32_bf16 v[86:89], v[90:93], v[86:89], v[48:51]
	v_mfma_f32_16x16x32_bf16 v[52:55], v[90:93], v[94:97], v[52:55]
	v_mfma_f32_16x16x32_bf16 v[56:59], v[90:93], v[116:119], v[56:59]
	v_mfma_f32_16x16x32_bf16 v[60:63], v[90:93], v[120:123], v[60:63]
	ds_read_b128 v[90:93], v114 offset:49152
	ds_read_b128 v[32:35], v113 offset:34816
	ds_read_b128 v[94:97], v114 offset:51200
	ds_read_b128 v[116:119], v114 offset:53248
	ds_read_b128 v[120:123], v114 offset:55296
	s_waitcnt lgkmcnt(0)
	v_mfma_f32_16x16x32_bf16 v[0:3], v[16:19], v[90:93], v[0:3]
	v_mfma_f32_16x16x32_bf16 v[4:7], v[16:19], v[94:97], v[4:7]
	v_mfma_f32_16x16x32_bf16 v[8:11], v[16:19], v[116:119], v[8:11]
	v_mfma_f32_16x16x32_bf16 v[16:19], v[16:19], v[120:123], v[12:15]
	v_mfma_f32_16x16x32_bf16 v[12:15], v[32:35], v[90:93], v[82:85]
	ds_read_b128 v[48:51], v113 offset:36864
	s_nop 1
	ds_read_b128 v[82:85], v113 offset:38912
	s_waitcnt vmcnt(0) lgkmcnt(0)
	s_barrier
	s_cbranch_vccnz .Lge6_exit1
	s_setprio 1
	v_mfma_f32_16x16x32_bf16 v[20:23], v[32:35], v[94:97], v[20:23]
	s_add_i32 m0, s52, 0x8000
	v_lshl_add_u64 v[246:247], s[2:3], 0, v[66:67]
	v_lshl_add_u64 v[246:247], v[246:247], 0, s[18:19]
	global_load_lds_dwordx4 v[246:247], off
	v_mfma_f32_16x16x32_bf16 v[24:27], v[32:35], v[116:119], v[24:27]
	s_add_i32 m0, s52, 0xc000
	v_lshl_add_u64 v[246:247], s[2:3], 0, v[74:75]
	v_lshl_add_u64 v[246:247], v[246:247], 0, s[26:27]
	global_load_lds_dwordx4 v[246:247], off
	v_mfma_f32_16x16x32_bf16 v[32:35], v[32:35], v[120:123], v[28:31]
	s_add_i32 m0, s52, 0x8400
	v_lshl_add_u64 v[246:247], s[2:3], 0, v[68:69]
	v_lshl_add_u64 v[246:247], v[246:247], 0, s[18:19]
	global_load_lds_dwordx4 v[246:247], off
	s_waitcnt lgkmcnt(0)
	v_mfma_f32_16x16x32_bf16 v[28:31], v[48:51], v[90:93], v[124:127]
	s_add_i32 m0, s52, 0xc400
	v_lshl_add_u64 v[246:247], s[2:3], 0, v[76:77]
	v_lshl_add_u64 v[246:247], v[246:247], 0, s[26:27]
	global_load_lds_dwordx4 v[246:247], off
	v_mfma_f32_16x16x32_bf16 v[36:39], v[48:51], v[94:97], v[36:39]
	s_add_i32 m0, s52, 0x8800
	v_lshl_add_u64 v[246:247], s[2:3], 0, v[70:71]
	v_lshl_add_u64 v[246:247], v[246:247], 0, s[18:19]
	global_load_lds_dwordx4 v[246:247], off
	v_mfma_f32_16x16x32_bf16 v[40:43], v[48:51], v[116:119], v[40:43]
	s_add_i32 m0, s52, 0xc800
	v_lshl_add_u64 v[246:247], s[2:3], 0, v[78:79]
	v_lshl_add_u64 v[246:247], v[246:247], 0, s[26:27]
	global_load_lds_dwordx4 v[246:247], off
	v_mfma_f32_16x16x32_bf16 v[48:51], v[48:51], v[120:123], v[44:47]
	s_add_i32 m0, s58, 0x8000
	v_lshl_add_u64 v[246:247], s[2:3], 0, v[72:73]
	v_lshl_add_u64 v[246:247], v[246:247], 0, s[18:19]
	global_load_lds_dwordx4 v[246:247], off
	v_mfma_f32_16x16x32_bf16 v[44:47], v[82:85], v[90:93], v[86:89]
	s_add_i32 m0, s58, 0xc000
	v_lshl_add_u64 v[246:247], s[2:3], 0, v[80:81]
	v_lshl_add_u64 v[246:247], v[246:247], 0, s[26:27]
	global_load_lds_dwordx4 v[246:247], off
	v_mfma_f32_16x16x32_bf16 v[52:55], v[82:85], v[94:97], v[52:55]
	v_mfma_f32_16x16x32_bf16 v[56:59], v[82:85], v[116:119], v[56:59]
	v_mfma_f32_16x16x32_bf16 v[60:63], v[82:85], v[120:123], v[60:63]
	s_cmpk_gt_u32 s51, 0x37f
	s_branch .Lge6_k0

; #define GBAR() do { asm volatile("s_waitcnt vmcnt(0) lgkmcnt(0)" ::: "memory"); __builtin_amdgcn_s_barrier(); } while (0)
; template <int EPI, bool GUARD>
; DEVI void gemm_tile(const Params& p, const bf16_t* __restrict__ A, int lda, const bf16_t* __restrict__ Bt, int ldb, int K,
;                           int row_base, int row_lo, int row_hi, int tile_n, int layer, int which, char* lds) {
;     ...
;   const int swz = c16 >> 1;
;   int koff[2];
; #pragma unroll
;   for (int ks = 0; ks < 2; ++ks) koff[ks] = ((ks * 4 + q4) ^ swz) << 4;
;   const int arow = (wr * 64 + c16) * 128, brow = 16384 + (wc * 64 + c16) * 128;
;     ...
;   GISSUE(0, 0); GBAR();
;   for (int k0 = 0; k0 < K; k0 += 128) {
;     GISSUE(k0 + 64, 1);
;     KSTEPS(0);
;     GBAR();
;     if (k0 + 128 < K) GISSUE(k0 + 128, 0);
;     KSTEPS(1);
;     GBAR();
;   }
.Lge6_k0:
	ds_read_b128 v[116:119], v64
	ds_read_b128 v[120:123], v112 offset:16384
	ds_read_b128 v[124:127], v64 offset:2048
	ds_read_b128 v[128:131], v112 offset:18432
	ds_read_b128 v[132:135], v112 offset:20480
	ds_read_b128 v[136:139], v112 offset:22528
	s_waitcnt lgkmcnt(0)
	v_mfma_f32_16x16x32_bf16 v[0:3], v[116:119], v[120:123], v[0:3]
	s_cselect_b64 s[4:5], -1, 0
	s_and_b64 vcc, exec, s[4:5]
	v_mfma_f32_16x16x32_bf16 v[4:7], v[116:119], v[128:131], v[4:7]
	v_mfma_f32_16x16x32_bf16 v[8:11], v[116:119], v[132:135], v[8:11]
	v_mfma_f32_16x16x32_bf16 v[16:19], v[116:119], v[136:139], v[16:19]
	s_setprio 0
	v_mfma_f32_16x16x32_bf16 v[116:119], v[124:127], v[120:123], v[12:15]
	v_mfma_f32_16x16x32_bf16 v[20:23], v[124:127], v[128:131], v[20:23]
	v_mfma_f32_16x16x32_bf16 v[24:27], v[124:127], v[132:135], v[24:27]
	v_mfma_f32_16x16x32_bf16 v[32:35], v[124:127], v[136:139], v[32:35]
	ds_read_b128 v[12:15], v64 offset:4096
	ds_read_b128 v[124:127], v64 offset:6144
	s_waitcnt lgkmcnt(0)
	v_mfma_f32_16x16x32_bf16 v[140:143], v[12:15], v[120:123], v[28:31]
	v_mfma_f32_16x16x32_bf16 v[36:39], v[12:15], v[128:131], v[36:39]
	v_mfma_f32_16x16x32_bf16 v[40:43], v[12:15], v[132:135], v[40:43]
	v_mfma_f32_16x16x32_bf16 v[48:51], v[12:15], v[136:139], v[48:51]
	ds_read_b128 v[12:15], v113
	v_mfma_f32_16x16x32_bf16 v[120:123], v[124:127], v[120:123], v[44:47]
	v_mfma_f32_16x16x32_bf16 v[52:55], v[124:127], v[128:131], v[52:55]
	v_mfma_f32_16x16x32_bf16 v[56:59], v[124:127], v[132:135], v[56:59]
	v_mfma_f32_16x16x32_bf16 v[60:63], v[124:127], v[136:139], v[60:63]
	ds_read_b128 v[124:127], v114 offset:16384
	ds_read_b128 v[28:31], v113 offset:2048
	ds_read_b128 v[128:131], v114 offset:18432
	ds_read_b128 v[132:135], v114 offset:20480
	ds_read_b128 v[136:139], v114 offset:22528
	s_waitcnt lgkmcnt(0)
	v_mfma_f32_16x16x32_bf16 v[0:3], v[12:15], v[124:127], v[0:3]
	v_mfma_f32_16x16x32_bf16 v[4:7], v[12:15], v[128:131], v[4:7]
	v_mfma_f32_16x16x32_bf16 v[8:11], v[12:15], v[132:135], v[8:11]
	v_mfma_f32_16x16x32_bf16 v[12:15], v[12:15], v[136:139], v[16:19]
	v_mfma_f32_16x16x32_bf16 v[16:19], v[28:31], v[124:127], v[116:119]
	ds_read_b128 v[44:47], v113 offset:4096
	s_nop 1
	ds_read_b128 v[116:119], v113 offset:6144
	s_waitcnt vmcnt(0) lgkmcnt(0)
	s_barrier
	s_cbranch_vccnz .Lge6_last0
	s_setprio 1
	v_mfma_f32_16x16x32_bf16 v[20:23], v[28:31], v[128:131], v[20:23]
	s_mov_b32 m0, s52
	v_lshl_add_u64 v[246:247], s[2:3], 0, v[66:67]
	v_lshl_add_u64 v[246:247], v[246:247], 0, s[28:29]
	global_load_lds_dwordx4 v[246:247], off
	v_mfma_f32_16x16x32_bf16 v[24:27], v[28:31], v[132:135], v[24:27]
	s_mov_b32 m0, s53
	v_lshl_add_u64 v[246:247], s[2:3], 0, v[74:75]
	v_lshl_add_u64 v[246:247], v[246:247], 0, s[30:31]
	global_load_lds_dwordx4 v[246:247], off
	v_mfma_f32_16x16x32_bf16 v[28:31], v[28:31], v[136:139], v[32:35]
	s_mov_b32 m0, s54
	v_lshl_add_u64 v[246:247], s[2:3], 0, v[68:69]
	v_lshl_add_u64 v[246:247], v[246:247], 0, s[28:29]
	global_load_lds_dwordx4 v[246:247], off
	s_waitcnt lgkmcnt(0)
	v_mfma_f32_16x16x32_bf16 v[32:35], v[44:47], v[124:127], v[140:143]
	s_mov_b32 m0, s55
	v_lshl_add_u64 v[246:247], s[2:3], 0, v[76:77]
	v_lshl_add_u64 v[246:247], v[246:247], 0, s[30:31]
	global_load_lds_dwordx4 v[246:247], off
	v_mfma_f32_16x16x32_bf16 v[36:39], v[44:47], v[128:131], v[36:39]
	s_mov_b32 m0, s56
	v_lshl_add_u64 v[246:247], s[2:3], 0, v[70:71]
	v_lshl_add_u64 v[246:247], v[246:247], 0, s[28:29]
	global_load_lds_dwordx4 v[246:247], off
	v_mfma_f32_16x16x32_bf16 v[40:43], v[44:47], v[132:135], v[40:43]
	s_mov_b32 m0, s57
	v_lshl_add_u64 v[246:247], s[2:3], 0, v[78:79]
	v_lshl_add_u64 v[246:247], v[246:247], 0, s[30:31]
	global_load_lds_dwordx4 v[246:247], off
	v_mfma_f32_16x16x32_bf16 v[44:47], v[44:47], v[136:139], v[48:51]
	s_mov_b32 m0, s58
	v_lshl_add_u64 v[246:247], s[2:3], 0, v[72:73]
	v_lshl_add_u64 v[246:247], v[246:247], 0, s[28:29]
	global_load_lds_dwordx4 v[246:247], off
	v_mfma_f32_16x16x32_bf16 v[48:51], v[116:119], v[124:127], v[120:123]
	s_mov_b32 m0, s59
	v_lshl_add_u64 v[246:247], s[2:3], 0, v[80:81]
	v_lshl_add_u64 v[246:247], v[246:247], 0, s[30:31]
	global_load_lds_dwordx4 v[246:247], off
	v_mfma_f32_16x16x32_bf16 v[52:55], v[116:119], v[128:131], v[52:55]
	v_mfma_f32_16x16x32_bf16 v[56:59], v[116:119], v[132:135], v[56:59]
	v_mfma_f32_16x16x32_bf16 v[60:63], v[116:119], v[136:139], v[60:63]
	s_branch .LBB0_1258

; #define GBAR() do { asm volatile("s_waitcnt vmcnt(0) lgkmcnt(0)" ::: "memory"); __builtin_amdgcn_s_barrier(); } while (0)
; template <int EPI, bool GUARD>
; DEVI void gemm_tile(const Params& p, const bf16_t* __restrict__ A, int lda, const bf16_t* __restrict__ Bt, int ldb, int K,
;                           int row_base, int row_lo, int row_hi, int tile_n, int layer, int which, char* lds) {
;     ...
;   const int swz = c16 >> 1;
;   int koff[2];
; #pragma unroll
;   for (int ks = 0; ks < 2; ++ks) koff[ks] = ((ks * 4 + q4) ^ swz) << 4;
;   const int arow = (wr * 64 + c16) * 128, brow = 16384 + (wc * 64 + c16) * 128;
;     ...
;   GISSUE(0, 0); GBAR();
;   for (int k0 = 0; k0 < K; k0 += 128) {
;     GISSUE(k0 + 64, 1);
;     KSTEPS(0);
;     GBAR();
;     if (k0 + 128 < K) GISSUE(k0 + 128, 0);
;     KSTEPS(1);
;     GBAR();
;   }
.LBB0_1336:
	ds_read_b128 v[82:85], v64 offset:32768
	ds_read_b128 v[86:89], v107 offset:49152
	ds_read_b128 v[90:93], v64 offset:34816
	ds_read_b128 v[94:97], v107 offset:51200
	ds_read_b128 v[110:113], v107 offset:53248
	ds_read_b128 v[114:117], v107 offset:55296
	s_addk_i32 s44, 0x80
	s_waitcnt lgkmcnt(0)
	v_mfma_f32_16x16x32_bf16 v[0:3], v[82:85], v[86:89], v[0:3]
	s_add_u32 s18, s18, 0x100
	s_addc_u32 s19, s19, 0
	s_andn2_b64 vcc, exec, s[20:21]
	v_mfma_f32_16x16x32_bf16 v[4:7], v[82:85], v[94:97], v[4:7]
	v_mfma_f32_16x16x32_bf16 v[8:11], v[82:85], v[110:113], v[8:11]
	v_mfma_f32_16x16x32_bf16 v[12:15], v[82:85], v[114:117], v[12:15]
	s_setprio 0
	v_mfma_f32_16x16x32_bf16 v[16:19], v[90:93], v[86:89], v[16:19]
	v_mfma_f32_16x16x32_bf16 v[20:23], v[90:93], v[94:97], v[20:23]
	v_mfma_f32_16x16x32_bf16 v[24:27], v[90:93], v[110:113], v[24:27]
	v_mfma_f32_16x16x32_bf16 v[28:31], v[90:93], v[114:117], v[28:31]
	ds_read_b128 v[82:85], v64 offset:36864
	ds_read_b128 v[90:93], v64 offset:38912
	s_waitcnt lgkmcnt(0)
	v_mfma_f32_16x16x32_bf16 v[118:121], v[82:85], v[86:89], v[32:35]
	s_nop 2
	ds_read_b128 v[32:35], v108 offset:32768
	v_mfma_f32_16x16x32_bf16 v[122:125], v[82:85], v[94:97], v[36:39]
	v_mfma_f32_16x16x32_bf16 v[126:129], v[82:85], v[110:113], v[40:43]
	v_mfma_f32_16x16x32_bf16 v[82:85], v[82:85], v[114:117], v[44:47]
	v_mfma_f32_16x16x32_bf16 v[86:89], v[90:93], v[86:89], v[48:51]
	v_mfma_f32_16x16x32_bf16 v[94:97], v[90:93], v[94:97], v[52:55]
	v_mfma_f32_16x16x32_bf16 v[110:113], v[90:93], v[110:113], v[56:59]
	v_mfma_f32_16x16x32_bf16 v[90:93], v[90:93], v[114:117], v[60:63]
	ds_read_b128 v[114:117], v109 offset:49152
	ds_read_b128 v[130:133], v108 offset:34816
	ds_read_b128 v[134:137], v109 offset:51200
	ds_read_b128 v[138:141], v109 offset:53248
	ds_read_b128 v[142:145], v109 offset:55296
	s_waitcnt lgkmcnt(0)
	v_mfma_f32_16x16x32_bf16 v[60:63], v[32:35], v[114:117], v[0:3]
	v_mfma_f32_16x16x32_bf16 v[52:55], v[32:35], v[138:141], v[8:11]
	s_nop 1
	ds_read_b128 v[0:3], v108 offset:36864
	ds_read_b128 v[8:11], v108 offset:38912
	s_waitcnt vmcnt(0) lgkmcnt(0)
	s_barrier
	s_cbranch_vccz .Lge7_exit1
	s_setprio 1
	v_mfma_f32_16x16x32_bf16 v[56:59], v[32:35], v[134:137], v[4:7]
	s_mov_b32 m0, s45
	v_lshl_add_u64 v[246:247], s[18:19], 0, v[66:67]
	v_lshl_add_u64 v[246:247], v[246:247], 0, s[2:3]
	global_load_lds_dwordx4 v[246:247], off
	v_mfma_f32_16x16x32_bf16 v[48:51], v[32:35], v[142:145], v[12:15]
	s_mov_b32 m0, s50
	v_lshl_add_u64 v[246:247], s[18:19], 0, v[74:75]
	v_lshl_add_u64 v[246:247], v[246:247], 0, s[4:5]
	global_load_lds_dwordx4 v[246:247], off
	v_mfma_f32_16x16x32_bf16 v[44:47], v[130:133], v[114:117], v[16:19]
	s_mov_b32 m0, s46
	v_lshl_add_u64 v[246:247], s[18:19], 0, v[68:69]
	v_lshl_add_u64 v[246:247], v[246:247], 0, s[2:3]
	global_load_lds_dwordx4 v[246:247], off
	v_mfma_f32_16x16x32_bf16 v[40:43], v[130:133], v[134:137], v[20:23]
	s_mov_b32 m0, s47
	v_lshl_add_u64 v[246:247], s[18:19], 0, v[76:77]
	v_lshl_add_u64 v[246:247], v[246:247], 0, s[4:5]
	global_load_lds_dwordx4 v[246:247], off
	v_mfma_f32_16x16x32_bf16 v[36:39], v[130:133], v[138:141], v[24:27]
	s_mov_b32 m0, s48
	v_lshl_add_u64 v[246:247], s[18:19], 0, v[70:71]
	v_lshl_add_u64 v[246:247], v[246:247], 0, s[2:3]
	global_load_lds_dwordx4 v[246:247], off
	v_mfma_f32_16x16x32_bf16 v[32:35], v[130:133], v[142:145], v[28:31]
	s_mov_b32 m0, s49
	v_lshl_add_u64 v[246:247], s[18:19], 0, v[78:79]
	v_lshl_add_u64 v[246:247], v[246:247], 0, s[4:5]
	global_load_lds_dwordx4 v[246:247], off
	s_waitcnt lgkmcnt(0)
	v_mfma_f32_16x16x32_bf16 v[28:31], v[0:3], v[114:117], v[118:121]
	s_mov_b32 m0, s51
	v_lshl_add_u64 v[246:247], s[18:19], 0, v[72:73]
	v_lshl_add_u64 v[246:247], v[246:247], 0, s[2:3]
	global_load_lds_dwordx4 v[246:247], off
	v_mfma_f32_16x16x32_bf16 v[24:27], v[0:3], v[134:137], v[122:125]
	s_mov_b32 m0, s52
	v_lshl_add_u64 v[246:247], s[18:19], 0, v[80:81]
	v_lshl_add_u64 v[246:247], v[246:247], 0, s[4:5]
	global_load_lds_dwordx4 v[246:247], off
	v_mfma_f32_16x16x32_bf16 v[16:19], v[0:3], v[138:141], v[126:129]
	v_mfma_f32_16x16x32_bf16 v[12:15], v[0:3], v[142:145], v[82:85]
	v_mfma_f32_16x16x32_bf16 v[4:7], v[8:11], v[114:117], v[86:89]
	v_mfma_f32_16x16x32_bf16 v[0:3], v[8:11], v[134:137], v[94:97]
	v_mfma_f32_16x16x32_bf16 v[20:23], v[8:11], v[138:141], v[110:113]
	v_mfma_f32_16x16x32_bf16 v[8:11], v[8:11], v[142:145], v[90:93]
	s_cmpk_gt_u32 s44, 0xa7f
	s_cselect_b64 s[20:21], -1, 0
	s_and_b64 vcc, exec, s[20:21]
	s_branch .Lge7_k0

; #define GBAR() do { asm volatile("s_waitcnt vmcnt(0) lgkmcnt(0)" ::: "memory"); __builtin_amdgcn_s_barrier(); } while (0)
; template <int EPI, bool GUARD>
; DEVI void gemm_tile(const Params& p, const bf16_t* __restrict__ A, int lda, const bf16_t* __restrict__ Bt, int ldb, int K,
;                           int row_base, int row_lo, int row_hi, int tile_n, int layer, int which, char* lds) {
;     ...
;   const int swz = c16 >> 1;
;   int koff[2];
; #pragma unroll
;   for (int ks = 0; ks < 2; ++ks) koff[ks] = ((ks * 4 + q4) ^ swz) << 4;
;   const int arow = (wr * 64 + c16) * 128, brow = 16384 + (wc * 64 + c16) * 128;
;     ...
;   GISSUE(0, 0); GBAR();
;   for (int k0 = 0; k0 < K; k0 += 128) {
;     GISSUE(k0 + 64, 1);
;     KSTEPS(0);
;     GBAR();
;     if (k0 + 128 < K) GISSUE(k0 + 128, 0);
;     KSTEPS(1);
;     GBAR();
;   }
.Lge7_k0:
	ds_read_b128 v[110:113], v64
	ds_read_b128 v[114:117], v107 offset:16384
	ds_read_b128 v[118:121], v64 offset:2048
	ds_read_b128 v[122:125], v107 offset:18432
	ds_read_b128 v[126:129], v107 offset:20480
	ds_read_b128 v[130:133], v107 offset:22528
	s_waitcnt lgkmcnt(0)
	v_mfma_f32_16x16x32_bf16 v[60:63], v[110:113], v[114:117], v[60:63]
	v_mfma_f32_16x16x32_bf16 v[56:59], v[110:113], v[122:125], v[56:59]
	v_mfma_f32_16x16x32_bf16 v[52:55], v[110:113], v[126:129], v[52:55]
	v_mfma_f32_16x16x32_bf16 v[48:51], v[110:113], v[130:133], v[48:51]
	s_setprio 0
	v_mfma_f32_16x16x32_bf16 v[44:47], v[118:121], v[114:117], v[44:47]
	v_mfma_f32_16x16x32_bf16 v[40:43], v[118:121], v[122:125], v[40:43]
	v_mfma_f32_16x16x32_bf16 v[36:39], v[118:121], v[126:129], v[36:39]
	v_mfma_f32_16x16x32_bf16 v[32:35], v[118:121], v[130:133], v[32:35]
	ds_read_b128 v[110:113], v64 offset:4096
	ds_read_b128 v[118:121], v64 offset:6144
	s_waitcnt lgkmcnt(0)
	v_mfma_f32_16x16x32_bf16 v[134:137], v[110:113], v[114:117], v[28:31]
	v_mfma_f32_16x16x32_bf16 v[138:141], v[110:113], v[122:125], v[24:27]
	v_mfma_f32_16x16x32_bf16 v[142:145], v[110:113], v[126:129], v[16:19]
	v_mfma_f32_16x16x32_bf16 v[110:113], v[110:113], v[130:133], v[12:15]
	s_nop 2
	ds_read_b128 v[12:15], v108
	v_mfma_f32_16x16x32_bf16 v[114:117], v[118:121], v[114:117], v[4:7]
	v_mfma_f32_16x16x32_bf16 v[122:125], v[118:121], v[122:125], v[0:3]
	v_mfma_f32_16x16x32_bf16 v[126:129], v[118:121], v[126:129], v[20:23]
	v_mfma_f32_16x16x32_bf16 v[118:121], v[118:121], v[130:133], v[8:11]
	ds_read_b128 v[130:133], v109 offset:16384
	ds_read_b128 v[28:31], v108 offset:2048
	ds_read_b128 v[146:149], v109 offset:18432
	s_waitcnt lgkmcnt(0)
	v_mfma_f32_16x16x32_bf16 v[0:3], v[12:15], v[130:133], v[60:63]
	v_mfma_f32_16x16x32_bf16 v[4:7], v[12:15], v[146:149], v[56:59]
	s_nop 2
	ds_read_b128 v[56:59], v109 offset:20480
	ds_read_b128 v[60:63], v109 offset:22528
	v_mfma_f32_16x16x32_bf16 v[16:19], v[28:31], v[130:133], v[44:47]
	s_nop 2
	ds_read_b128 v[44:47], v108 offset:4096
	ds_read_b128 v[150:153], v108 offset:6144
	s_waitcnt vmcnt(0) lgkmcnt(0)
	s_barrier
	s_cbranch_vccnz .Lge7_last0
	s_setprio 1
	s_waitcnt lgkmcnt(0)
	v_mfma_f32_16x16x32_bf16 v[8:11], v[12:15], v[56:59], v[52:55]
	s_mov_b32 m0, s36
	v_lshl_add_u64 v[246:247], s[18:19], 0, v[66:67]
	v_lshl_add_u64 v[246:247], v[246:247], 0, s[6:7]
	global_load_lds_dwordx4 v[246:247], off
	v_mfma_f32_16x16x32_bf16 v[12:15], v[12:15], v[60:63], v[48:51]
	s_mov_b32 m0, s37
	v_lshl_add_u64 v[246:247], s[18:19], 0, v[74:75]
	v_lshl_add_u64 v[246:247], v[246:247], 0, s[8:9]
	global_load_lds_dwordx4 v[246:247], off
	v_mfma_f32_16x16x32_bf16 v[20:23], v[28:31], v[146:149], v[40:43]
	s_mov_b32 m0, s38
	v_lshl_add_u64 v[246:247], s[18:19], 0, v[68:69]
	v_lshl_add_u64 v[246:247], v[246:247], 0, s[6:7]
	global_load_lds_dwordx4 v[246:247], off
	v_mfma_f32_16x16x32_bf16 v[24:27], v[28:31], v[56:59], v[36:39]
	s_mov_b32 m0, s39
	v_lshl_add_u64 v[246:247], s[18:19], 0, v[76:77]
	v_lshl_add_u64 v[246:247], v[246:247], 0, s[8:9]
	global_load_lds_dwordx4 v[246:247], off
	v_mfma_f32_16x16x32_bf16 v[28:31], v[28:31], v[60:63], v[32:35]
	s_mov_b32 m0, s40
	v_lshl_add_u64 v[246:247], s[18:19], 0, v[70:71]
	v_lshl_add_u64 v[246:247], v[246:247], 0, s[6:7]
	global_load_lds_dwordx4 v[246:247], off
	v_mfma_f32_16x16x32_bf16 v[32:35], v[44:47], v[130:133], v[134:137]
	s_mov_b32 m0, s41
	v_lshl_add_u64 v[246:247], s[18:19], 0, v[78:79]
	v_lshl_add_u64 v[246:247], v[246:247], 0, s[8:9]
	global_load_lds_dwordx4 v[246:247], off
	v_mfma_f32_16x16x32_bf16 v[36:39], v[44:47], v[146:149], v[138:141]
	s_mov_b32 m0, s42
	v_lshl_add_u64 v[246:247], s[18:19], 0, v[72:73]
	v_lshl_add_u64 v[246:247], v[246:247], 0, s[6:7]
	global_load_lds_dwordx4 v[246:247], off
	v_mfma_f32_16x16x32_bf16 v[40:43], v[44:47], v[56:59], v[142:145]
	s_mov_b32 m0, s43
	v_lshl_add_u64 v[246:247], s[18:19], 0, v[80:81]
	v_lshl_add_u64 v[246:247], v[246:247], 0, s[8:9]
	global_load_lds_dwordx4 v[246:247], off
	v_mfma_f32_16x16x32_bf16 v[44:47], v[44:47], v[60:63], v[110:113]
	v_mfma_f32_16x16x32_bf16 v[48:51], v[150:153], v[130:133], v[114:117]
	v_mfma_f32_16x16x32_bf16 v[52:55], v[150:153], v[146:149], v[122:125]
	v_mfma_f32_16x16x32_bf16 v[56:59], v[150:153], v[56:59], v[126:129]
	v_mfma_f32_16x16x32_bf16 v[60:63], v[150:153], v[60:63], v[118:121]
	s_branch .LBB0_1336
